# v25 + only the A-operand (streamed once) LDS-DMA loads of the S5 GEMMs marked nt; weight loads keep default L2 policy
# speedup vs baseline: 1.0072x; 1.0072x over previous
; #define PG8_STAGE(bufoff, gbase, voff) do { _Pragma("unroll") for (int _i = 0; _i < 2; ++_i) \
;         __builtin_amdgcn_global_load_lds((const unsigned*)((const char*)(gbase) + (voff)[_i]), (PG8_LAS unsigned*)(lds + (bufoff) + ldsw + _i * 8192), 16, 0, 0); } while (0)
; #define PG8_WAIT_V(n) asm volatile("s_waitcnt vmcnt(" #n ")" ::: "memory")
; #define PG8_BAR __builtin_amdgcn_s_barrier()
; template <class Epi, class Sched, bool ALIGN_EPI = false, bool SP2 = false>
; __device__ __forceinline__ void gemm_phase(PG8_LAS unsigned char* lds, const Gemm g, const Sched& S, const Epi& E, const int tid) {
;     ...
;     if constexpr (SP2) {
;         PG8_STAGE(PG8_SB(0, 0), cB, voffB); PG8_STAGE(PG8_SB(0, 1), cB + hstepB, voffB); PG8_STAGE(PG8_SA(0, 0), cA, voffA); PG8_STAGE(PG8_SA(0, 1), cA + hstepA, voffA);
;         if (wr == 1) PG8_BAR;
;         PG8_WAIT_V(2); PG8_BAR;
;         PG8_STAGE(PG8_SB(1, 0), cB + kstep, voffB); PG8_STAGE(PG8_SA(1, 0), cA + kstep, voffA); PG8_STAGE(PG8_SB(1, 1), cB + hstepB + kstep, voffB);
;         PG8_WAIT_V(6); PG8_BAR;
.LBB0_269:
	v_and_b32_e32 v70, 15, v0
	v_bfe_u32 v71, v0, 4, 2
	v_lshlrev_b32_e32 v1, 6, v70
	v_lshlrev_b32_e32 v0, 2, v0
	s_and_b32 s48, s1, 3
	v_lshl_or_b32 v1, v71, 4, v1
	s_lshl_b32 s1, s34, 13
	v_and_b32_e32 v0, 32, v0
	v_lshl_add_u64 v[2:3], s[26:27], 0, v[204:205]
	v_mov_b32_e32 v65, v205
	v_bitop3_b32 v10, s1, v1, v0 bitop3:0xf6
	s_lshl_b32 s1, s48, 12
	v_lshl_add_u64 v[4:5], s[26:27], 0, v[64:65]
	v_mov_b32_e32 v69, v205
	v_bitop3_b32 v72, s1, v1, v0 bitop3:0xf6
	s_add_i32 m0, s36, 0x18000
	v_lshl_add_u64 v[0:1], v[2:3], 0, s[82:83]
	v_lshl_add_u64 v[6:7], s[24:25], 0, v[68:69]
	v_mov_b32_e32 v67, v205
	s_waitcnt vmcnt(2)
	s_barrier
	global_load_lds_dwordx4 v[0:1], off
	v_lshl_add_u64 v[0:1], v[4:5], 0, s[82:83]
	s_add_i32 m0, s36, 0x1a000
	s_add_i32 s49, s36, 0x8000
	s_add_i32 s50, s36, 0xa000
	v_lshl_add_u64 v[8:9], s[24:25], 0, v[66:67]
	global_load_lds_dwordx4 v[0:1], off
	v_lshl_add_u64 v[0:1], v[6:7], 0, s[82:83]
	s_mov_b32 m0, s49
	s_add_u32 s6, s26, 0x10080
	global_load_lds_dwordx4 v[0:1], off
	v_lshl_add_u64 v[0:1], v[8:9], 0, s[82:83]
	s_mov_b32 m0, s50
	s_addc_u32 s7, s27, 0
	s_add_i32 s54, s36, 0x1c000
	global_load_lds_dwordx4 v[0:1], off
	v_lshl_add_u64 v[0:1], s[6:7], 0, v[204:205]
	s_mov_b32 m0, s54
	s_add_i32 s55, s36, 0x1e000
	global_load_lds_dwordx4 v[0:1], off nt
	v_lshl_add_u64 v[0:1], s[6:7], 0, v[64:65]
	s_mov_b32 m0, s55
	s_cmpk_lt_u32 s0, 0x100
	global_load_lds_dwordx4 v[0:1], off nt
	s_waitcnt vmcnt(6)
	v_readlane_b32 s18, v255, 43
	s_cselect_b64 s[16:17], -1, 0
	v_add_u32_e32 v73, 0, v10
	v_readlane_b32 s19, v255, 44
	v_readlane_b32 s57, v255, 21
	s_barrier
	s_branch .LBB0_272

; #define PG8_STAGE(bufoff, gbase, voff) do { _Pragma("unroll") for (int _i = 0; _i < 2; ++_i) \
;         __builtin_amdgcn_global_load_lds((const unsigned*)((const char*)(gbase) + (voff)[_i]), (PG8_LAS unsigned*)(lds + (bufoff) + ldsw + _i * 8192), 16, 0, 0); } while (0)
; #define PG8_LDA(dst, b, h) do { _Pragma("unroll") for (int m = 0; m < 4; ++m) _Pragma("unroll") for (int k = 0; k < 2; ++k) dst[m][k] = *(const PG8_LAS bf16x8*)(lds + PG8_SA(b, h) + aoff + m * 2048 + k * 1024); } while (0)
; #define PG8_LDB(dst, b, h) do { _Pragma("unroll") for (int n = 0; n < 2; ++n) _Pragma("unroll") for (int k = 0; k < 2; ++k) dst[n][k] = *(const PG8_LAS bf16x8*)(lds + PG8_SB(b, h) + boff + n * 2048 + k * 1024); } while (0)
; #define PG8_MMA(ai, bj, At, Bt) do { __builtin_amdgcn_s_setprio(1); _Pragma("unroll") for (int m = 0; m < 4; ++m) _Pragma("unroll") for (int n = 0; n < 2; ++n) _Pragma("unroll") for (int k = 0; k < 2; ++k) \
;         acc[ai][bj][m][n] = __builtin_amdgcn_mfma_f32_16x16x32_bf16(Bt[n][k], At[m][k], acc[ai][bj][m][n], 0, 0, 0); __builtin_amdgcn_s_setprio(0); } while (0)
; #define PG8_WAIT_V(n) asm volatile("s_waitcnt vmcnt(" #n ")" ::: "memory")
; #define PG8_WAIT_L(n) asm volatile("s_waitcnt lgkmcnt(" #n ")" ::: "memory")
; #define PG8_BAR __builtin_amdgcn_s_barrier()
; #define PG8_SCHED __builtin_amdgcn_sched_barrier(0)
; template <class Epi, class Sched, bool ALIGN_EPI = false, bool SP2 = false>
; __device__ __forceinline__ void gemm_phase(PG8_LAS unsigned char* lds, const Gemm g, const Sched& S, const Epi& E, const int tid) {
;     ...
;             if constexpr (SP2) {
;             PG8_LDB(B0, 0, 0); PG8_LDB(B1, 0, 1); PG8_SCHED; PG8_LDA(At, 0, 0); PG8_STAGE(PG8_SA(1, 1), a1 + hstepA, voffA);
;             PG8_WAIT_V(8); PG8_WAIT_L(0); PG8_BAR; PG8_MMA(0, 0, At, B0); PG8_MMA(0, 1, At, B1); PG8_BAR; PG8_SCHED;
;             PG8_LDA(At, 0, 1); PG8_STAGE(PG8_SB(0, 0), b2, voffB); PG8_STAGE(PG8_SB(0, 1), b2 + hstepB, voffB); PG8_STAGE(PG8_SA(0, 0), a2, voffA);
;             PG8_WAIT_V(8); PG8_WAIT_L(0); PG8_BAR; PG8_MMA(1, 0, At, B0); PG8_MMA(1, 1, At, B1); PG8_BAR; PG8_SCHED;
.LBB0_282:
	s_add_i32 s60, 0, 0x10000
	v_add_u32_e32 v132, s60, v72
	ds_read_b128 v[0:3], v132
	ds_read_b128 v[4:7], v132 offset:1024
	ds_read_b128 v[8:11], v132 offset:2048
	ds_read_b128 v[12:15], v132 offset:3072
	s_add_u32 s58, s24, 0x18080
	s_addc_u32 s59, s25, 0
	s_add_i32 s61, s36, 0xc000
	v_lshl_add_u64 v[48:49], s[58:59], 0, v[68:69]
	s_mov_b32 m0, s61
	s_add_i32 s21, s36, 0xe000
	ds_read_b128 v[16:19], v73
	ds_read_b128 v[20:23], v73 offset:1024
	ds_read_b128 v[24:27], v73 offset:2048
	ds_read_b128 v[28:31], v73 offset:3072
	ds_read_b128 v[32:35], v73 offset:4096
	ds_read_b128 v[36:39], v73 offset:5120
	ds_read_b128 v[40:43], v73 offset:6144
	ds_read_b128 v[44:47], v73 offset:7168
	global_load_lds_dwordx4 v[48:49], off nt
	v_lshl_add_u64 v[48:49], s[58:59], 0, v[66:67]
	s_mov_b32 m0, s21
	s_nop 0
	global_load_lds_dwordx4 v[48:49], off nt
	s_waitcnt vmcnt(8)
	s_waitcnt lgkmcnt(0)
	s_barrier
	s_setprio 1
	s_waitcnt lgkmcnt(0)
	v_mfma_f32_16x16x32_bf16 v[48:51], v[0:3], v[16:19], 0
	v_mfma_f32_16x16x32_bf16 v[16:19], v[8:11], v[16:19], 0
	v_mfma_f32_16x16x32_bf16 v[48:51], v[4:7], v[20:23], v[48:51]
	v_mfma_f32_16x16x32_bf16 v[16:19], v[12:15], v[20:23], v[16:19]
	v_mfma_f32_16x16x32_bf16 v[20:23], v[0:3], v[24:27], 0
	v_mfma_f32_16x16x32_bf16 v[24:27], v[8:11], v[24:27], 0
	v_mfma_f32_16x16x32_bf16 v[20:23], v[4:7], v[28:31], v[20:23]
	v_mfma_f32_16x16x32_bf16 v[24:27], v[12:15], v[28:31], v[24:27]
	v_mfma_f32_16x16x32_bf16 v[28:31], v[0:3], v[32:35], 0
	v_mfma_f32_16x16x32_bf16 v[32:35], v[8:11], v[32:35], 0
	v_mfma_f32_16x16x32_bf16 v[28:31], v[4:7], v[36:39], v[28:31]
	v_mfma_f32_16x16x32_bf16 v[32:35], v[12:15], v[36:39], v[32:35]
	v_mfma_f32_16x16x32_bf16 v[36:39], v[0:3], v[40:43], 0
	v_mfma_f32_16x16x32_bf16 v[40:43], v[8:11], v[40:43], 0
	v_mfma_f32_16x16x32_bf16 v[36:39], v[4:7], v[44:47], v[36:39]
	v_mfma_f32_16x16x32_bf16 v[40:43], v[12:15], v[44:47], v[40:43]
	s_setprio 0
	s_setprio 1
	s_setprio 0
	s_barrier
	s_add_i32 s60, s60, s35
	v_lshl_add_u64 v[122:123], s[26:27], 0, v[204:205]
	s_add_i32 s58, s60, 0x2000
	v_lshl_add_u64 v[90:91], v[122:123], 0, s[84:85]
	s_mov_b32 m0, s60
	v_lshl_add_u64 v[124:125], s[26:27], 0, v[64:65]
	s_add_u32 s62, s26, 0x10100
	ds_read_b128 v[44:47], v73 offset:16384
	ds_read_b128 v[52:55], v73 offset:17408
	ds_read_b128 v[56:59], v73 offset:18432
	ds_read_b128 v[60:63], v73 offset:19456
	ds_read_b128 v[74:77], v73 offset:20480
	ds_read_b128 v[78:81], v73 offset:21504
	ds_read_b128 v[82:85], v73 offset:22528
	ds_read_b128 v[86:89], v73 offset:23552
	global_load_lds_dwordx4 v[90:91], off
	v_lshl_add_u64 v[90:91], v[124:125], 0, s[84:85]
	s_mov_b32 m0, s58
	s_addc_u32 s63, s27, 0
	global_load_lds_dwordx4 v[90:91], off
	v_lshl_add_u64 v[90:91], s[62:63], 0, v[204:205]
	s_mov_b32 m0, s37
	v_lshl_add_u64 v[126:127], s[24:25], 0, v[68:69]
	global_load_lds_dwordx4 v[90:91], off
	v_lshl_add_u64 v[90:91], s[62:63], 0, v[64:65]
	s_mov_b32 m0, s42
	v_lshl_add_u64 v[128:129], s[24:25], 0, v[66:67]
	global_load_lds_dwordx4 v[90:91], off
	v_lshl_add_u64 v[90:91], v[126:127], 0, s[84:85]
	s_mov_b32 m0, s36
	s_nop 0
	global_load_lds_dwordx4 v[90:91], off nt
	v_lshl_add_u64 v[90:91], v[128:129], 0, s[84:85]
	s_mov_b32 m0, s43
	s_nop 0
	global_load_lds_dwordx4 v[90:91], off nt
	s_waitcnt vmcnt(8)
	s_waitcnt lgkmcnt(0)
	s_barrier
	s_setprio 1
	s_waitcnt lgkmcnt(0)
	v_mfma_f32_16x16x32_bf16 v[90:93], v[0:3], v[44:47], 0
	v_mfma_f32_16x16x32_bf16 v[44:47], v[8:11], v[44:47], 0
	v_mfma_f32_16x16x32_bf16 v[90:93], v[4:7], v[52:55], v[90:93]
	v_mfma_f32_16x16x32_bf16 v[44:47], v[12:15], v[52:55], v[44:47]
	v_mfma_f32_16x16x32_bf16 v[52:55], v[0:3], v[56:59], 0
	v_mfma_f32_16x16x32_bf16 v[56:59], v[8:11], v[56:59], 0
	v_mfma_f32_16x16x32_bf16 v[52:55], v[4:7], v[60:63], v[52:55]
	v_mfma_f32_16x16x32_bf16 v[56:59], v[12:15], v[60:63], v[56:59]
	v_mfma_f32_16x16x32_bf16 v[60:63], v[0:3], v[74:77], 0
	v_mfma_f32_16x16x32_bf16 v[0:3], v[0:3], v[82:85], 0
	v_mfma_f32_16x16x32_bf16 v[60:63], v[4:7], v[78:81], v[60:63]
	v_mfma_f32_16x16x32_bf16 v[0:3], v[4:7], v[86:89], v[0:3]
	v_mfma_f32_16x16x32_bf16 v[4:7], v[8:11], v[82:85], 0
	v_mfma_f32_16x16x32_bf16 v[74:77], v[8:11], v[74:77], 0
	v_mfma_f32_16x16x32_bf16 v[4:7], v[12:15], v[86:89], v[4:7]
	v_mfma_f32_16x16x32_bf16 v[74:77], v[12:15], v[78:81], v[74:77]
	s_setprio 0
	s_setprio 1
	s_setprio 0
	s_barrier
	s_add_i32 s59, 0, 0x18000
	v_add_u32_e32 v133, s59, v72
	ds_read_b128 v[8:11], v133
	ds_read_b128 v[12:15], v133 offset:1024
	ds_read_b128 v[78:81], v133 offset:2048
	ds_read_b128 v[82:85], v133 offset:3072
	s_add_u32 s62, s24, 0x18100
	s_addc_u32 s63, s25, 0
	s_mov_b32 m0, s46
	v_lshl_add_u64 v[130:131], s[62:63], 0, v[68:69]
	ds_read_b128 v[86:89], v73 offset:32768
	ds_read_b128 v[94:97], v73 offset:33792
	ds_read_b128 v[98:101], v73 offset:34816
	ds_read_b128 v[102:105], v73 offset:35840
	ds_read_b128 v[106:109], v73 offset:36864
	ds_read_b128 v[110:113], v73 offset:37888
	ds_read_b128 v[114:117], v73 offset:38912
	ds_read_b128 v[118:121], v73 offset:39936
	global_load_lds_dwordx4 v[130:131], off nt
	v_lshl_add_u64 v[130:131], s[62:63], 0, v[66:67]
	s_mov_b32 m0, s47
	s_nop 0
	global_load_lds_dwordx4 v[130:131], off nt
	s_waitcnt vmcnt(8)
	s_waitcnt lgkmcnt(0)
	s_barrier
; #define PG8_STAGE(bufoff, gbase, voff) do { _Pragma("unroll") for (int _i = 0; _i < 2; ++_i) \
;         __builtin_amdgcn_global_load_lds((const unsigned*)((const char*)(gbase) + (voff)[_i]), (PG8_LAS unsigned*)(lds + (bufoff) + ldsw + _i * 8192), 16, 0, 0); } while (0)
; #define PG8_LDA(dst, b, h) do { _Pragma("unroll") for (int m = 0; m < 4; ++m) _Pragma("unroll") for (int k = 0; k < 2; ++k) dst[m][k] = *(const PG8_LAS bf16x8*)(lds + PG8_SA(b, h) + aoff + m * 2048 + k * 1024); } while (0)
; #define PG8_LDB(dst, b, h) do { _Pragma("unroll") for (int n = 0; n < 2; ++n) _Pragma("unroll") for (int k = 0; k < 2; ++k) dst[n][k] = *(const PG8_LAS bf16x8*)(lds + PG8_SB(b, h) + boff + n * 2048 + k * 1024); } while (0)
; #define PG8_MMA(ai, bj, At, Bt) do { __builtin_amdgcn_s_setprio(1); _Pragma("unroll") for (int m = 0; m < 4; ++m) _Pragma("unroll") for (int n = 0; n < 2; ++n) _Pragma("unroll") for (int k = 0; k < 2; ++k) \
;         acc[ai][bj][m][n] = __builtin_amdgcn_mfma_f32_16x16x32_bf16(Bt[n][k], At[m][k], acc[ai][bj][m][n], 0, 0, 0); __builtin_amdgcn_s_setprio(0); } while (0)
; #define PG8_WAIT_V(n) asm volatile("s_waitcnt vmcnt(" #n ")" ::: "memory")
; #define PG8_WAIT_L(n) asm volatile("s_waitcnt lgkmcnt(" #n ")" ::: "memory")
; #define PG8_BAR __builtin_amdgcn_s_barrier()
; #define PG8_SCHED __builtin_amdgcn_sched_barrier(0)
; template <class Epi, class Sched, bool ALIGN_EPI = false, bool SP2 = false>
; __device__ __forceinline__ void gemm_phase(PG8_LAS unsigned char* lds, const Gemm g, const Sched& S, const Epi& E, const int tid) {
;     ...
;             PG8_WAIT_V(8); PG8_WAIT_L(0); PG8_BAR; PG8_MMA(1, 0, At, B0); PG8_MMA(1, 1, At, B1); PG8_BAR; PG8_SCHED;
;             PG8_LDB(B0, 1, 0); PG8_LDB(B1, 1, 1); PG8_SCHED; PG8_LDA(At, 1, 0); PG8_STAGE(PG8_SA(0, 1), a2 + hstepA, voffA);
;             PG8_WAIT_V(8); PG8_WAIT_L(0); PG8_BAR; PG8_MMA(0, 0, At, B0); PG8_MMA(0, 1, At, B1); PG8_BAR; PG8_SCHED;
;             PG8_LDA(At, 1, 1); PG8_STAGE(PG8_SB(1, 0), b3, voffB); PG8_STAGE(PG8_SB(1, 1), b3 + hstepB, voffB); PG8_STAGE(PG8_SA(1, 0), a3, voffA);
;             PG8_WAIT_V(8); PG8_WAIT_L(0); PG8_BAR; PG8_MMA(1, 0, At, B0); PG8_MMA(1, 1, At, B1); PG8_BAR; PG8_SCHED;
	s_setprio 1
	s_waitcnt lgkmcnt(0)
	v_mfma_f32_16x16x32_bf16 v[48:51], v[8:11], v[86:89], v[48:51]
	v_mfma_f32_16x16x32_bf16 v[16:19], v[78:81], v[86:89], v[16:19]
	v_mfma_f32_16x16x32_bf16 v[20:23], v[8:11], v[98:101], v[20:23]
	v_mfma_f32_16x16x32_bf16 v[24:27], v[78:81], v[98:101], v[24:27]
	v_mfma_f32_16x16x32_bf16 v[28:31], v[8:11], v[106:109], v[28:31]
	v_mfma_f32_16x16x32_bf16 v[32:35], v[78:81], v[106:109], v[32:35]
	v_mfma_f32_16x16x32_bf16 v[36:39], v[8:11], v[114:117], v[36:39]
	v_mfma_f32_16x16x32_bf16 v[40:43], v[78:81], v[114:117], v[40:43]
	v_mfma_f32_16x16x32_bf16 v[48:51], v[12:15], v[94:97], v[48:51]
	v_mfma_f32_16x16x32_bf16 v[16:19], v[82:85], v[94:97], v[16:19]
	v_mfma_f32_16x16x32_bf16 v[20:23], v[12:15], v[102:105], v[20:23]
	v_mfma_f32_16x16x32_bf16 v[24:27], v[82:85], v[102:105], v[24:27]
	v_mfma_f32_16x16x32_bf16 v[28:31], v[12:15], v[110:113], v[28:31]
	v_mfma_f32_16x16x32_bf16 v[32:35], v[82:85], v[110:113], v[32:35]
	v_mfma_f32_16x16x32_bf16 v[36:39], v[12:15], v[118:121], v[36:39]
	v_mfma_f32_16x16x32_bf16 v[40:43], v[82:85], v[118:121], v[40:43]
	s_setprio 0
	s_setprio 1
	s_setprio 0
	s_barrier
	s_add_i32 s62, s59, s35
	s_add_i32 s59, s62, 0x2000
	v_lshl_add_u64 v[122:123], v[122:123], 0, s[94:95]
	s_mov_b32 m0, s62
	s_add_u32 s26, s26, 0x10180
	ds_read_b128 v[86:89], v73 offset:49152
	ds_read_b128 v[94:97], v73 offset:50176
	ds_read_b128 v[98:101], v73 offset:51200
	ds_read_b128 v[102:105], v73 offset:52224
	ds_read_b128 v[106:109], v73 offset:53248
	ds_read_b128 v[110:113], v73 offset:54272
	ds_read_b128 v[114:117], v73 offset:55296
	ds_read_b128 v[118:121], v73 offset:56320
	global_load_lds_dwordx4 v[122:123], off
	v_lshl_add_u64 v[122:123], v[124:125], 0, s[94:95]
	s_mov_b32 m0, s59
	s_addc_u32 s27, s27, 0
	global_load_lds_dwordx4 v[122:123], off
	v_lshl_add_u64 v[122:123], s[26:27], 0, v[204:205]
	s_mov_b32 m0, s54
	s_nop 0
	global_load_lds_dwordx4 v[122:123], off
	v_lshl_add_u64 v[122:123], s[26:27], 0, v[64:65]
	s_mov_b32 m0, s55
	s_nop 0
	global_load_lds_dwordx4 v[122:123], off
	v_lshl_add_u64 v[122:123], v[126:127], 0, s[94:95]
	s_mov_b32 m0, s49
	s_nop 0
	global_load_lds_dwordx4 v[122:123], off nt
	v_lshl_add_u64 v[122:123], v[128:129], 0, s[94:95]
	s_mov_b32 m0, s50
	s_nop 0
	global_load_lds_dwordx4 v[122:123], off nt
	s_waitcnt vmcnt(8)
	s_waitcnt lgkmcnt(0)
	s_barrier
	s_setprio 1
	s_waitcnt lgkmcnt(0)
	v_mfma_f32_16x16x32_bf16 v[44:47], v[78:81], v[86:89], v[44:47]
	v_mfma_f32_16x16x32_bf16 v[52:55], v[8:11], v[98:101], v[52:55]
	v_mfma_f32_16x16x32_bf16 v[56:59], v[78:81], v[98:101], v[56:59]
	v_mfma_f32_16x16x32_bf16 v[60:63], v[8:11], v[106:109], v[60:63]
	v_mfma_f32_16x16x32_bf16 v[0:3], v[8:11], v[114:117], v[0:3]
	v_mfma_f32_16x16x32_bf16 v[4:7], v[78:81], v[114:117], v[4:7]
	v_mfma_f32_16x16x32_bf16 v[90:93], v[8:11], v[86:89], v[90:93]
	v_mfma_f32_16x16x32_bf16 v[44:47], v[82:85], v[94:97], v[44:47]
	v_mfma_f32_16x16x32_bf16 v[52:55], v[12:15], v[102:105], v[52:55]
	v_mfma_f32_16x16x32_bf16 v[56:59], v[82:85], v[102:105], v[56:59]
	v_mfma_f32_16x16x32_bf16 v[60:63], v[12:15], v[110:113], v[60:63]
	v_mfma_f32_16x16x32_bf16 v[74:77], v[78:81], v[106:109], v[74:77]
	v_mfma_f32_16x16x32_bf16 v[0:3], v[12:15], v[118:121], v[0:3]
	v_mfma_f32_16x16x32_bf16 v[4:7], v[82:85], v[118:121], v[4:7]
	v_mfma_f32_16x16x32_bf16 v[90:93], v[12:15], v[94:97], v[90:93]
	v_mfma_f32_16x16x32_bf16 v[74:77], v[82:85], v[110:113], v[74:77]
	s_setprio 0
	s_setprio 1
	s_setprio 0
	s_barrier
	ds_read_b128 v[8:11], v132
	ds_read_b128 v[12:15], v132 offset:1024
	ds_read_b128 v[78:81], v132 offset:2048
	ds_read_b128 v[82:85], v132 offset:3072
	s_add_u32 s24, s24, 0x18180
	s_addc_u32 s25, s25, 0
	s_mov_b32 m0, s61
	v_lshl_add_u64 v[122:123], s[24:25], 0, v[68:69]
	ds_read_b128 v[86:89], v73
	ds_read_b128 v[94:97], v73 offset:1024
	ds_read_b128 v[98:101], v73 offset:2048
	ds_read_b128 v[102:105], v73 offset:3072
	ds_read_b128 v[106:109], v73 offset:4096
	ds_read_b128 v[110:113], v73 offset:5120
	ds_read_b128 v[114:117], v73 offset:6144
	ds_read_b128 v[118:121], v73 offset:7168
	global_load_lds_dwordx4 v[122:123], off nt
	v_lshl_add_u64 v[122:123], s[24:25], 0, v[66:67]
	s_mov_b32 m0, s21
	s_nop 0
	global_load_lds_dwordx4 v[122:123], off nt
	s_waitcnt vmcnt(8)
	s_waitcnt lgkmcnt(0)
	s_barrier
	s_setprio 1
	s_waitcnt lgkmcnt(0)
	v_mfma_f32_16x16x32_bf16 v[28:31], v[8:11], v[106:109], v[28:31]
	v_mfma_f32_16x16x32_bf16 v[48:51], v[8:11], v[86:89], v[48:51]
	v_mfma_f32_16x16x32_bf16 v[16:19], v[78:81], v[86:89], v[16:19]
	v_mfma_f32_16x16x32_bf16 v[86:89], v[12:15], v[110:113], v[28:31]
	v_mfma_f32_16x16x32_bf16 v[28:31], v[78:81], v[106:109], v[32:35]
	v_mfma_f32_16x16x32_bf16 v[32:35], v[82:85], v[110:113], v[28:31]
	v_mfma_f32_16x16x32_bf16 v[28:31], v[8:11], v[114:117], v[36:39]
	v_mfma_f32_16x16x32_bf16 v[48:51], v[12:15], v[94:97], v[48:51]
	v_mfma_f32_16x16x32_bf16 v[16:19], v[82:85], v[94:97], v[16:19]
	v_mfma_f32_16x16x32_bf16 v[20:23], v[8:11], v[98:101], v[20:23]
	v_mfma_f32_16x16x32_bf16 v[24:27], v[78:81], v[98:101], v[24:27]
	v_mfma_f32_16x16x32_bf16 v[94:97], v[12:15], v[118:121], v[28:31]
	v_mfma_f32_16x16x32_bf16 v[28:31], v[78:81], v[114:117], v[40:43]
	v_mfma_f32_16x16x32_bf16 v[20:23], v[12:15], v[102:105], v[20:23]
	v_mfma_f32_16x16x32_bf16 v[24:27], v[82:85], v[102:105], v[24:27]
	v_mfma_f32_16x16x32_bf16 v[40:43], v[82:85], v[118:121], v[28:31]
	s_setprio 0
	s_setprio 1
	s_setprio 0
	s_barrier
; #define PG8_STAGE(bufoff, gbase, voff) do { _Pragma("unroll") for (int _i = 0; _i < 2; ++_i) \
;         __builtin_amdgcn_global_load_lds((const unsigned*)((const char*)(gbase) + (voff)[_i]), (PG8_LAS unsigned*)(lds + (bufoff) + ldsw + _i * 8192), 16, 0, 0); } while (0)
; #define PG8_LDA(dst, b, h) do { _Pragma("unroll") for (int m = 0; m < 4; ++m) _Pragma("unroll") for (int k = 0; k < 2; ++k) dst[m][k] = *(const PG8_LAS bf16x8*)(lds + PG8_SA(b, h) + aoff + m * 2048 + k * 1024); } while (0)
; #define PG8_LDB(dst, b, h) do { _Pragma("unroll") for (int n = 0; n < 2; ++n) _Pragma("unroll") for (int k = 0; k < 2; ++k) dst[n][k] = *(const PG8_LAS bf16x8*)(lds + PG8_SB(b, h) + boff + n * 2048 + k * 1024); } while (0)
; #define PG8_WAIT_V(n) asm volatile("s_waitcnt vmcnt(" #n ")" ::: "memory")
; template <class Epi, class Sched, bool ALIGN_EPI = false, bool SP2 = false>
; __device__ __forceinline__ void gemm_phase(PG8_LAS unsigned char* lds, const Gemm g, const Sched& S, const Epi& E, const int tid) {
;     ...
;             const char* a2 = last ? nA : cA + (size_t)(t + 2) * kstep; const char* b2 = last ? nB : cB + (size_t)(t + 2) * kstep;
;             const char* a3 = a2 + kstep; const char* b3 = b2 + kstep;
;             if (last && has_next) S.a_ready(nxt);
;             if constexpr (SP2) {
;             PG8_LDB(B0, 0, 0); PG8_LDB(B1, 0, 1); PG8_SCHED; PG8_LDA(At, 0, 0); PG8_STAGE(PG8_SA(1, 1), a1 + hstepA, voffA);
;             PG8_WAIT_V(8); PG8_WAIT_L(0); PG8_BAR; PG8_MMA(0, 0, At, B0); PG8_MMA(0, 1, At, B1); PG8_BAR; PG8_SCHED;
;             PG8_LDA(At, 0, 1); PG8_STAGE(PG8_SB(0, 0), b2, voffB); PG8_STAGE(PG8_SB(0, 1), b2 + hstepB, voffB); PG8_STAGE(PG8_SA(0, 0), a2, voffA);
;             PG8_WAIT_V(8); PG8_WAIT_L(0); PG8_BAR; PG8_MMA(1, 0, At, B0); PG8_MMA(1, 1, At, B1); PG8_BAR; PG8_SCHED;
;             PG8_LDB(B0, 1, 0); PG8_LDB(B1, 1, 1); PG8_SCHED; PG8_LDA(At, 1, 0); PG8_STAGE(PG8_SA(0, 1), a2 + hstepA, voffA);
;             PG8_WAIT_V(8); PG8_WAIT_L(0); PG8_BAR; PG8_MMA(0, 0, At, B0); PG8_MMA(0, 1, At, B1); PG8_BAR; PG8_SCHED;
;             PG8_LDA(At, 1, 1); PG8_STAGE(PG8_SB(1, 0), b3, voffB); PG8_STAGE(PG8_SB(1, 1), b3 + hstepB, voffB); PG8_STAGE(PG8_SA(1, 0), a3, voffA);
;             PG8_WAIT_V(8); PG8_WAIT_L(0); PG8_BAR; PG8_MMA(1, 0, At, B0); PG8_MMA(1, 1, At, B1); PG8_BAR; PG8_SCHED;
;     ...
;         if constexpr (ALIGN_EPI) { if (wr == 0) PG8_BAR; }
	s_mov_b32 m0, s60
	v_lshl_add_u64 v[134:135], s[22:23], 0, v[204:205]
	s_add_u32 s24, s22, 0x10000
	ds_read_b128 v[28:31], v73 offset:16384
	ds_read_b128 v[36:39], v73 offset:17408
	ds_read_b128 v[98:101], v73 offset:18432
	ds_read_b128 v[102:105], v73 offset:19456
	ds_read_b128 v[106:109], v73 offset:20480
	ds_read_b128 v[110:113], v73 offset:21504
	ds_read_b128 v[114:117], v73 offset:22528
	ds_read_b128 v[118:121], v73 offset:23552
	global_load_lds_dwordx4 v[134:135], off
	v_lshl_add_u64 v[136:137], s[22:23], 0, v[64:65]
	s_mov_b32 m0, s58
	s_addc_u32 s25, s23, 0
	global_load_lds_dwordx4 v[136:137], off
	v_lshl_add_u64 v[122:123], s[24:25], 0, v[204:205]
	s_mov_b32 m0, s37
	v_lshl_add_u64 v[138:139], s[0:1], 0, v[68:69]
	global_load_lds_dwordx4 v[122:123], off
	v_lshl_add_u64 v[122:123], s[24:25], 0, v[64:65]
	s_mov_b32 m0, s42
	v_lshl_add_u64 v[140:141], s[0:1], 0, v[66:67]
	global_load_lds_dwordx4 v[122:123], off
	s_mov_b32 m0, s36
	s_nop 0
	global_load_lds_dwordx4 v[138:139], off nt
	s_mov_b32 m0, s43
	s_nop 0
	global_load_lds_dwordx4 v[140:141], off nt
	s_waitcnt vmcnt(8)
	s_waitcnt lgkmcnt(0)
	s_barrier
	s_setprio 1
	s_waitcnt lgkmcnt(0)
	v_mfma_f32_16x16x32_bf16 v[90:93], v[8:11], v[28:31], v[90:93]
	v_mfma_f32_16x16x32_bf16 v[28:31], v[78:81], v[28:31], v[44:47]
	v_mfma_f32_16x16x32_bf16 v[44:47], v[82:85], v[36:39], v[28:31]
	v_mfma_f32_16x16x32_bf16 v[28:31], v[8:11], v[98:101], v[52:55]
	v_mfma_f32_16x16x32_bf16 v[52:55], v[12:15], v[102:105], v[28:31]
	v_mfma_f32_16x16x32_bf16 v[28:31], v[78:81], v[98:101], v[56:59]
	v_mfma_f32_16x16x32_bf16 v[98:101], v[82:85], v[102:105], v[28:31]
	v_mfma_f32_16x16x32_bf16 v[28:31], v[8:11], v[106:109], v[60:63]
	v_mfma_f32_16x16x32_bf16 v[0:3], v[8:11], v[114:117], v[0:3]
	v_mfma_f32_16x16x32_bf16 v[102:105], v[12:15], v[110:113], v[28:31]
	v_mfma_f32_16x16x32_bf16 v[28:31], v[78:81], v[106:109], v[74:77]
	v_mfma_f32_16x16x32_bf16 v[106:109], v[12:15], v[118:121], v[0:3]
	v_mfma_f32_16x16x32_bf16 v[0:3], v[78:81], v[114:117], v[4:7]
	v_mfma_f32_16x16x32_bf16 v[90:93], v[12:15], v[36:39], v[90:93]
	v_mfma_f32_16x16x32_bf16 v[74:77], v[82:85], v[110:113], v[28:31]
	v_mfma_f32_16x16x32_bf16 v[78:81], v[82:85], v[118:121], v[0:3]
	s_setprio 0
	s_setprio 1
	s_setprio 0
	s_barrier
	ds_read_b128 v[82:85], v133
	ds_read_b128 v[110:113], v133 offset:1024
	ds_read_b128 v[114:117], v133 offset:2048
	ds_read_b128 v[118:121], v133 offset:3072
	s_add_u32 s24, s0, 0x18000
	s_addc_u32 s25, s1, 0
	s_mov_b32 m0, s46
	v_lshl_add_u64 v[28:29], s[24:25], 0, v[68:69]
	ds_read_b128 v[0:3], v73 offset:32768
	ds_read_b128 v[4:7], v73 offset:33792
	ds_read_b128 v[8:11], v73 offset:34816
	ds_read_b128 v[12:15], v73 offset:35840
	ds_read_b128 v[56:59], v73 offset:36864
	ds_read_b128 v[60:63], v73 offset:37888
	ds_read_b128 v[122:125], v73 offset:38912
	ds_read_b128 v[126:129], v73 offset:39936
	global_load_lds_dwordx4 v[28:29], off nt
	v_lshl_add_u64 v[28:29], s[24:25], 0, v[66:67]
	s_mov_b32 m0, s47
	s_nop 0
	global_load_lds_dwordx4 v[28:29], off nt
	s_waitcnt vmcnt(8)
	s_waitcnt lgkmcnt(0)
	s_barrier
	s_setprio 1
	s_waitcnt lgkmcnt(0)
	v_mfma_f32_16x16x32_bf16 v[28:31], v[82:85], v[0:3], v[48:51]
	v_mfma_f32_16x16x32_bf16 v[0:3], v[114:117], v[0:3], v[16:19]
	v_mfma_f32_16x16x32_bf16 v[36:39], v[118:121], v[4:7], v[0:3]
	v_mfma_f32_16x16x32_bf16 v[0:3], v[82:85], v[8:11], v[20:23]
	v_mfma_f32_16x16x32_bf16 v[16:19], v[110:113], v[12:15], v[0:3]
	v_mfma_f32_16x16x32_bf16 v[0:3], v[114:117], v[8:11], v[24:27]
	v_mfma_f32_16x16x32_bf16 v[20:23], v[118:121], v[12:15], v[0:3]
	v_mfma_f32_16x16x32_bf16 v[0:3], v[82:85], v[56:59], v[86:89]
	v_mfma_f32_16x16x32_bf16 v[8:11], v[110:113], v[60:63], v[0:3]
	v_mfma_f32_16x16x32_bf16 v[0:3], v[114:117], v[56:59], v[32:35]
	v_mfma_f32_16x16x32_bf16 v[28:31], v[110:113], v[4:7], v[28:31]
	v_mfma_f32_16x16x32_bf16 v[12:15], v[118:121], v[60:63], v[0:3]
	v_mfma_f32_16x16x32_bf16 v[0:3], v[82:85], v[122:125], v[94:97]
	v_mfma_f32_16x16x32_bf16 v[4:7], v[114:117], v[122:125], v[40:43]
	v_mfma_f32_16x16x32_bf16 v[0:3], v[110:113], v[126:129], v[0:3]
	v_mfma_f32_16x16x32_bf16 v[4:7], v[118:121], v[126:129], v[4:7]
	s_setprio 0
	s_setprio 1
	s_setprio 0
	s_barrier
	s_mov_b32 m0, s62
	v_lshl_add_u64 v[48:49], v[134:135], 0, s[82:83]
	s_add_u32 s24, s22, 0x10080
	ds_read_b128 v[24:27], v73 offset:49152
	ds_read_b128 v[32:35], v73 offset:50176
	ds_read_b128 v[40:43], v73 offset:51200
	ds_read_b128 v[86:89], v73 offset:52224
	ds_read_b128 v[94:97], v73 offset:53248
	ds_read_b128 v[122:125], v73 offset:54272
	ds_read_b128 v[126:129], v73 offset:55296
	ds_read_b128 v[130:133], v73 offset:56320
	global_load_lds_dwordx4 v[48:49], off
	v_lshl_add_u64 v[48:49], v[136:137], 0, s[82:83]
	s_mov_b32 m0, s59
	s_addc_u32 s25, s23, 0
	global_load_lds_dwordx4 v[48:49], off
	v_lshl_add_u64 v[48:49], s[24:25], 0, v[204:205]
	s_mov_b32 m0, s54
	s_nop 0
	global_load_lds_dwordx4 v[48:49], off
	v_lshl_add_u64 v[48:49], s[24:25], 0, v[64:65]
	s_mov_b32 m0, s55
	s_nop 0
	global_load_lds_dwordx4 v[48:49], off
	v_lshl_add_u64 v[48:49], v[138:139], 0, s[82:83]
	s_mov_b32 m0, s49
	s_nop 0
	global_load_lds_dwordx4 v[48:49], off nt
	v_lshl_add_u64 v[48:49], v[140:141], 0, s[82:83]
	s_mov_b32 m0, s50
	s_nop 0
	global_load_lds_dwordx4 v[48:49], off nt
	s_waitcnt vmcnt(8)
	s_waitcnt lgkmcnt(0)
	s_barrier
	s_setprio 1
	s_waitcnt lgkmcnt(0)
	v_mfma_f32_16x16x32_bf16 v[48:51], v[82:85], v[24:27], v[90:93]
	v_mfma_f32_16x16x32_bf16 v[24:27], v[114:117], v[24:27], v[44:47]
	v_mfma_f32_16x16x32_bf16 v[60:63], v[118:121], v[32:35], v[24:27]
	v_mfma_f32_16x16x32_bf16 v[24:27], v[82:85], v[40:43], v[52:55]
	v_mfma_f32_16x16x32_bf16 v[56:59], v[110:113], v[32:35], v[48:51]
	v_mfma_f32_16x16x32_bf16 v[48:51], v[110:113], v[86:89], v[24:27]
	v_mfma_f32_16x16x32_bf16 v[24:27], v[114:117], v[40:43], v[98:101]
	v_mfma_f32_16x16x32_bf16 v[52:55], v[118:121], v[86:89], v[24:27]
	v_mfma_f32_16x16x32_bf16 v[24:27], v[82:85], v[94:97], v[102:105]
	v_mfma_f32_16x16x32_bf16 v[40:43], v[110:113], v[122:125], v[24:27]
	v_mfma_f32_16x16x32_bf16 v[24:27], v[114:117], v[94:97], v[74:77]
	v_mfma_f32_16x16x32_bf16 v[44:47], v[118:121], v[122:125], v[24:27]
	v_mfma_f32_16x16x32_bf16 v[24:27], v[82:85], v[126:129], v[106:109]
	v_mfma_f32_16x16x32_bf16 v[32:35], v[114:117], v[126:129], v[78:81]
	v_mfma_f32_16x16x32_bf16 v[24:27], v[110:113], v[130:133], v[24:27]
	v_mfma_f32_16x16x32_bf16 v[32:35], v[118:121], v[130:133], v[32:35]
	s_setprio 0
	s_setprio 1
	s_setprio 0
	s_barrier
	s_andn2_b64 vcc, exec, s[16:17]
	s_cbranch_vccnz .LBB0_284
	s_barrier

; #define PG8_STAGE(bufoff, gbase, voff) do { _Pragma("unroll") for (int _i = 0; _i < 2; ++_i) \
;         __builtin_amdgcn_global_load_lds((const unsigned*)((const char*)(gbase) + (voff)[_i]), (PG8_LAS unsigned*)(lds + (bufoff) + ldsw + _i * 8192), 16, 0, 0); } while (0)
; #define PG8_WAIT_V(n) asm volatile("s_waitcnt vmcnt(" #n ")" ::: "memory")
; #define PG8_BAR __builtin_amdgcn_s_barrier()
; template <class Epi, class Sched, bool ALIGN_EPI = false, bool SP2 = false>
; __device__ __forceinline__ void gemm_phase(PG8_LAS unsigned char* lds, const Gemm g, const Sched& S, const Epi& E, const int tid) {
;     ...
;     if constexpr (SP2) {
;         PG8_STAGE(PG8_SB(0, 0), cB, voffB); PG8_STAGE(PG8_SB(0, 1), cB + hstepB, voffB); PG8_STAGE(PG8_SA(0, 0), cA, voffA); PG8_STAGE(PG8_SA(0, 1), cA + hstepA, voffA);
;         if (wr == 1) PG8_BAR;
;         PG8_WAIT_V(2); PG8_BAR;
;         PG8_STAGE(PG8_SB(1, 0), cB + kstep, voffB); PG8_STAGE(PG8_SA(1, 0), cA + kstep, voffA); PG8_STAGE(PG8_SB(1, 1), cB + hstepB + kstep, voffB);
;         PG8_WAIT_V(6); PG8_BAR;
.LBB0_313:
	v_and_b32_e32 v138, 15, v0
	v_bfe_u32 v139, v0, 4, 2
	v_lshlrev_b32_e32 v1, 6, v138
	v_lshlrev_b32_e32 v0, 2, v0
	v_mov_b32_e32 v133, v205
	s_and_b32 s34, s1, 3
	v_lshl_or_b32 v1, v139, 4, v1
	s_lshl_b32 s1, s26, 13
	v_and_b32_e32 v0, 32, v0
	v_lshl_add_u64 v[2:3], s[20:21], 0, v[132:133]
	v_mov_b32_e32 v129, v205
	v_bitop3_b32 v10, s1, v1, v0 bitop3:0xf6
	s_lshl_b32 s1, s34, 12
	v_lshl_add_u64 v[4:5], s[20:21], 0, v[128:129]
	v_mov_b32_e32 v135, v205
	v_bitop3_b32 v140, s1, v1, v0 bitop3:0xf6
	s_add_i32 m0, s28, 0x18000
	v_lshl_add_u64 v[0:1], v[2:3], 0, s[82:83]
	v_lshl_add_u64 v[6:7], s[18:19], 0, v[134:135]
	v_mov_b32_e32 v131, v205
	s_waitcnt vmcnt(2)
	s_barrier
	global_load_lds_dwordx4 v[0:1], off
	v_lshl_add_u64 v[0:1], v[4:5], 0, s[82:83]
	s_add_i32 m0, s28, 0x1a000
	s_add_i32 s35, s28, 0x8000
	s_add_i32 s36, s28, 0xa000
	v_lshl_add_u64 v[8:9], s[18:19], 0, v[130:131]
	global_load_lds_dwordx4 v[0:1], off
	v_lshl_add_u64 v[0:1], v[6:7], 0, s[82:83]
	s_mov_b32 m0, s35
	s_add_u32 s4, s20, 0x18080
	global_load_lds_dwordx4 v[0:1], off
	v_lshl_add_u64 v[0:1], v[8:9], 0, s[82:83]
	s_mov_b32 m0, s36
	s_addc_u32 s5, s21, 0
	global_load_lds_dwordx4 v[0:1], off
	s_add_i32 m0, s28, 0x1c000
	v_lshl_add_u64 v[0:1], s[4:5], 0, v[132:133]
	global_load_lds_dwordx4 v[0:1], off nt
	v_lshl_add_u64 v[0:1], s[4:5], 0, v[128:129]
	s_add_i32 m0, s28, 0x1e000
	s_cmpk_lt_u32 s0, 0x100
	global_load_lds_dwordx4 v[0:1], off nt
	s_waitcnt vmcnt(6)
	v_readlane_b32 s14, v255, 43
	v_add_u32_e32 v141, 0, v10
	s_cselect_b64 s[12:13], -1, 0
	v_readlane_b32 s15, v255, 44
	v_readlane_b32 s42, v255, 21
	s_barrier
	s_branch .LBB0_316

; #define PG8_STAGE(bufoff, gbase, voff) do { _Pragma("unroll") for (int _i = 0; _i < 2; ++_i) \
;         __builtin_amdgcn_global_load_lds((const unsigned*)((const char*)(gbase) + (voff)[_i]), (PG8_LAS unsigned*)(lds + (bufoff) + ldsw + _i * 8192), 16, 0, 0); } while (0)
; #define PG8_LDA(dst, b, h) do { _Pragma("unroll") for (int m = 0; m < 4; ++m) _Pragma("unroll") for (int k = 0; k < 2; ++k) dst[m][k] = *(const PG8_LAS bf16x8*)(lds + PG8_SA(b, h) + aoff + m * 2048 + k * 1024); } while (0)
; #define PG8_LDB(dst, b, h) do { _Pragma("unroll") for (int n = 0; n < 2; ++n) _Pragma("unroll") for (int k = 0; k < 2; ++k) dst[n][k] = *(const PG8_LAS bf16x8*)(lds + PG8_SB(b, h) + boff + n * 2048 + k * 1024); } while (0)
; #define PG8_MMA(ai, bj, At, Bt) do { __builtin_amdgcn_s_setprio(1); _Pragma("unroll") for (int m = 0; m < 4; ++m) _Pragma("unroll") for (int n = 0; n < 2; ++n) _Pragma("unroll") for (int k = 0; k < 2; ++k) \
;         acc[ai][bj][m][n] = __builtin_amdgcn_mfma_f32_16x16x32_bf16(Bt[n][k], At[m][k], acc[ai][bj][m][n], 0, 0, 0); __builtin_amdgcn_s_setprio(0); } while (0)
; #define PG8_WAIT_V(n) asm volatile("s_waitcnt vmcnt(" #n ")" ::: "memory")
; #define PG8_WAIT_L(n) asm volatile("s_waitcnt lgkmcnt(" #n ")" ::: "memory")
; #define PG8_BAR __builtin_amdgcn_s_barrier()
; #define PG8_SCHED __builtin_amdgcn_sched_barrier(0)
; template <class Epi, class Sched, bool ALIGN_EPI = false, bool SP2 = false>
; __device__ __forceinline__ void gemm_phase(PG8_LAS unsigned char* lds, const Gemm g, const Sched& S, const Epi& E, const int tid) {
;     ...
;             if constexpr (SP2) {
;             PG8_LDB(B0, 0, 0); PG8_LDB(B1, 0, 1); PG8_SCHED; PG8_LDA(At, 0, 0); PG8_STAGE(PG8_SA(1, 1), a1 + hstepA, voffA);
;             PG8_WAIT_V(8); PG8_WAIT_L(0); PG8_BAR; PG8_MMA(0, 0, At, B0); PG8_MMA(0, 1, At, B1); PG8_BAR; PG8_SCHED;
;             PG8_LDA(At, 0, 1); PG8_STAGE(PG8_SB(0, 0), b2, voffB); PG8_STAGE(PG8_SB(0, 1), b2 + hstepB, voffB); PG8_STAGE(PG8_SA(0, 0), a2, voffA);
;             PG8_WAIT_V(8); PG8_WAIT_L(0); PG8_BAR; PG8_MMA(1, 0, At, B0); PG8_MMA(1, 1, At, B1); PG8_BAR; PG8_SCHED;
.LBB0_326:
	s_add_i32 s47, 0, 0x10000
	s_add_i32 s49, 0, 0x14000
	v_add_u32_e32 v8, s47, v140
	v_add_u32_e32 v9, s49, v140
	ds_read_b128 v[10:13], v8
	ds_read_b128 v[14:17], v8 offset:1024
	ds_read_b128 v[18:21], v8 offset:2048
	ds_read_b128 v[22:25], v8 offset:3072
	ds_read_b128 v[26:29], v9
	ds_read_b128 v[30:33], v9 offset:1024
	ds_read_b128 v[34:37], v9 offset:2048
	ds_read_b128 v[38:41], v9 offset:3072
	s_add_u32 s54, s18, 0x18080
	s_addc_u32 s55, s19, 0
	s_add_i32 s57, s28, 0xc000
	v_lshl_add_u64 v[66:67], s[54:55], 0, v[134:135]
	s_mov_b32 m0, s57
	s_add_i32 s43, s28, 0xe000
	ds_read_b128 v[0:3], v141
	ds_read_b128 v[4:7], v141 offset:1024
	ds_read_b128 v[42:45], v141 offset:2048
	ds_read_b128 v[46:49], v141 offset:3072
	ds_read_b128 v[50:53], v141 offset:4096
	ds_read_b128 v[54:57], v141 offset:5120
	ds_read_b128 v[58:61], v141 offset:6144
	ds_read_b128 v[62:65], v141 offset:7168
	global_load_lds_dwordx4 v[66:67], off nt
	v_lshl_add_u64 v[66:67], s[54:55], 0, v[130:131]
	s_mov_b32 m0, s43
	s_nop 0
	global_load_lds_dwordx4 v[66:67], off nt
	s_waitcnt vmcnt(8)
	s_waitcnt lgkmcnt(0)
	s_barrier
	s_setprio 1
	s_waitcnt lgkmcnt(0)
	v_mfma_f32_16x16x32_bf16 v[66:69], v[10:13], v[0:3], 0
	v_mfma_f32_16x16x32_bf16 v[70:73], v[18:21], v[0:3], 0
	v_mfma_f32_16x16x32_bf16 v[74:77], v[10:13], v[42:45], 0
	v_mfma_f32_16x16x32_bf16 v[78:81], v[18:21], v[42:45], 0
	v_mfma_f32_16x16x32_bf16 v[82:85], v[10:13], v[50:53], 0
	v_mfma_f32_16x16x32_bf16 v[86:89], v[18:21], v[50:53], 0
	v_mfma_f32_16x16x32_bf16 v[90:93], v[10:13], v[58:61], 0
	v_mfma_f32_16x16x32_bf16 v[94:97], v[18:21], v[58:61], 0
	v_mfma_f32_16x16x32_bf16 v[66:69], v[14:17], v[4:7], v[66:69]
	v_mfma_f32_16x16x32_bf16 v[70:73], v[22:25], v[4:7], v[70:73]
	v_mfma_f32_16x16x32_bf16 v[74:77], v[14:17], v[46:49], v[74:77]
	v_mfma_f32_16x16x32_bf16 v[78:81], v[22:25], v[46:49], v[78:81]
	v_mfma_f32_16x16x32_bf16 v[82:85], v[14:17], v[54:57], v[82:85]
	v_mfma_f32_16x16x32_bf16 v[86:89], v[22:25], v[54:57], v[86:89]
	v_mfma_f32_16x16x32_bf16 v[90:93], v[14:17], v[62:65], v[90:93]
	v_mfma_f32_16x16x32_bf16 v[94:97], v[22:25], v[62:65], v[94:97]
	s_setprio 0
	s_setprio 1
	v_mfma_f32_16x16x32_bf16 v[98:101], v[26:29], v[0:3], 0
	v_mfma_f32_16x16x32_bf16 v[0:3], v[34:37], v[0:3], 0
	v_mfma_f32_16x16x32_bf16 v[102:105], v[38:41], v[4:7], v[0:3]
	v_mfma_f32_16x16x32_bf16 v[0:3], v[26:29], v[42:45], 0
	v_mfma_f32_16x16x32_bf16 v[106:109], v[30:33], v[46:49], v[0:3]
	v_mfma_f32_16x16x32_bf16 v[0:3], v[34:37], v[42:45], 0
	v_mfma_f32_16x16x32_bf16 v[42:45], v[38:41], v[46:49], v[0:3]
	v_mfma_f32_16x16x32_bf16 v[0:3], v[26:29], v[50:53], 0
	v_mfma_f32_16x16x32_bf16 v[46:49], v[30:33], v[54:57], v[0:3]
	v_mfma_f32_16x16x32_bf16 v[0:3], v[34:37], v[50:53], 0
	v_mfma_f32_16x16x32_bf16 v[50:53], v[38:41], v[54:57], v[0:3]
	v_mfma_f32_16x16x32_bf16 v[0:3], v[26:29], v[58:61], 0
	v_mfma_f32_16x16x32_bf16 v[54:57], v[30:33], v[62:65], v[0:3]
	v_mfma_f32_16x16x32_bf16 v[0:3], v[34:37], v[58:61], 0
	v_mfma_f32_16x16x32_bf16 v[98:101], v[30:33], v[4:7], v[98:101]
	v_mfma_f32_16x16x32_bf16 v[58:61], v[38:41], v[62:65], v[0:3]
	s_setprio 0
	s_barrier
	s_nop 3
	v_lshl_add_u64 v[0:1], s[20:21], 0, v[132:133]
	s_add_i32 s54, s47, s27
	v_lshl_add_u64 v[2:3], v[0:1], 0, s[84:85]
	s_mov_b32 m0, s54
	s_add_i32 s47, s54, 0x2000
	ds_read_b128 v[62:65], v141 offset:16384
	ds_read_b128 v[110:113], v141 offset:17408
	ds_read_b128 v[114:117], v141 offset:18432
	ds_read_b128 v[118:121], v141 offset:19456
	ds_read_b128 v[122:125], v141 offset:20480
	ds_read_b128 v[142:145], v141 offset:21504
	ds_read_b128 v[146:149], v141 offset:22528
	ds_read_b128 v[150:153], v141 offset:23552
	global_load_lds_dwordx4 v[2:3], off
	v_lshl_add_u64 v[2:3], s[20:21], 0, v[128:129]
	s_add_u32 s58, s20, 0x18100
	v_lshl_add_u64 v[4:5], v[2:3], 0, s[84:85]
	s_mov_b32 m0, s47
	s_addc_u32 s59, s21, 0
	s_add_i32 s49, s49, s27
	global_load_lds_dwordx4 v[4:5], off
	v_lshl_add_u64 v[4:5], s[58:59], 0, v[132:133]
	s_mov_b32 m0, s49
	s_add_i32 s50, s49, 0x2000
	global_load_lds_dwordx4 v[4:5], off
	v_lshl_add_u64 v[4:5], s[58:59], 0, v[128:129]
	s_mov_b32 m0, s50
	s_nop 0
	global_load_lds_dwordx4 v[4:5], off
	v_lshl_add_u64 v[4:5], s[18:19], 0, v[134:135]
	v_lshl_add_u64 v[6:7], v[4:5], 0, s[84:85]
	s_mov_b32 m0, s28
	s_nop 0
	global_load_lds_dwordx4 v[6:7], off nt
	v_lshl_add_u64 v[6:7], s[18:19], 0, v[130:131]
	v_lshl_add_u64 v[126:127], v[6:7], 0, s[84:85]
	s_mov_b32 m0, s29
	s_nop 0
	global_load_lds_dwordx4 v[126:127], off nt
	s_waitcnt vmcnt(8)
	s_waitcnt lgkmcnt(0)
	s_barrier
	s_setprio 1
	s_waitcnt lgkmcnt(0)
	v_mfma_f32_16x16x32_bf16 v[154:157], v[10:13], v[62:65], 0
	v_mfma_f32_16x16x32_bf16 v[162:165], v[10:13], v[114:117], 0
	v_mfma_f32_16x16x32_bf16 v[170:173], v[10:13], v[122:125], 0
	v_mfma_f32_16x16x32_bf16 v[10:13], v[10:13], v[146:149], 0
	v_mfma_f32_16x16x32_bf16 v[154:157], v[14:17], v[110:113], v[154:157]
	v_mfma_f32_16x16x32_bf16 v[158:161], v[18:21], v[62:65], 0
	v_mfma_f32_16x16x32_bf16 v[162:165], v[14:17], v[118:121], v[162:165]
	v_mfma_f32_16x16x32_bf16 v[166:169], v[18:21], v[114:117], 0
	v_mfma_f32_16x16x32_bf16 v[170:173], v[14:17], v[142:145], v[170:173]
	v_mfma_f32_16x16x32_bf16 v[174:177], v[18:21], v[122:125], 0
	v_mfma_f32_16x16x32_bf16 v[12:15], v[14:17], v[150:153], v[10:13]
	v_mfma_f32_16x16x32_bf16 v[16:19], v[18:21], v[146:149], 0
	v_mfma_f32_16x16x32_bf16 v[16:19], v[22:25], v[150:153], v[16:19]
	v_mfma_f32_16x16x32_bf16 v[158:161], v[22:25], v[110:113], v[158:161]
	v_mfma_f32_16x16x32_bf16 v[166:169], v[22:25], v[118:121], v[166:169]
	v_mfma_f32_16x16x32_bf16 v[174:177], v[22:25], v[142:145], v[174:177]
	s_setprio 0
	s_setprio 1
	v_mfma_f32_16x16x32_bf16 v[20:23], v[26:29], v[62:65], 0
	v_mfma_f32_16x16x32_bf16 v[62:65], v[34:37], v[62:65], 0
	v_mfma_f32_16x16x32_bf16 v[20:23], v[30:33], v[110:113], v[20:23]
	v_mfma_f32_16x16x32_bf16 v[62:65], v[38:41], v[110:113], v[62:65]
	v_mfma_f32_16x16x32_bf16 v[110:113], v[26:29], v[114:117], 0
	v_mfma_f32_16x16x32_bf16 v[114:117], v[34:37], v[114:117], 0
	v_mfma_f32_16x16x32_bf16 v[110:113], v[30:33], v[118:121], v[110:113]
	v_mfma_f32_16x16x32_bf16 v[114:117], v[38:41], v[118:121], v[114:117]
	v_mfma_f32_16x16x32_bf16 v[118:121], v[26:29], v[122:125], 0
	v_mfma_f32_16x16x32_bf16 v[24:27], v[26:29], v[146:149], 0
	v_mfma_f32_16x16x32_bf16 v[118:121], v[30:33], v[142:145], v[118:121]
	v_mfma_f32_16x16x32_bf16 v[122:125], v[34:37], v[122:125], 0
	v_mfma_f32_16x16x32_bf16 v[24:27], v[30:33], v[150:153], v[24:27]
	v_mfma_f32_16x16x32_bf16 v[28:31], v[34:37], v[146:149], 0
	v_mfma_f32_16x16x32_bf16 v[122:125], v[38:41], v[142:145], v[122:125]
	v_mfma_f32_16x16x32_bf16 v[28:31], v[38:41], v[150:153], v[28:31]
	s_setprio 0
	s_barrier
; #define PG8_STAGE(bufoff, gbase, voff) do { _Pragma("unroll") for (int _i = 0; _i < 2; ++_i) \
;         __builtin_amdgcn_global_load_lds((const unsigned*)((const char*)(gbase) + (voff)[_i]), (PG8_LAS unsigned*)(lds + (bufoff) + ldsw + _i * 8192), 16, 0, 0); } while (0)
; #define PG8_LDA(dst, b, h) do { _Pragma("unroll") for (int m = 0; m < 4; ++m) _Pragma("unroll") for (int k = 0; k < 2; ++k) dst[m][k] = *(const PG8_LAS bf16x8*)(lds + PG8_SA(b, h) + aoff + m * 2048 + k * 1024); } while (0)
; #define PG8_LDB(dst, b, h) do { _Pragma("unroll") for (int n = 0; n < 2; ++n) _Pragma("unroll") for (int k = 0; k < 2; ++k) dst[n][k] = *(const PG8_LAS bf16x8*)(lds + PG8_SB(b, h) + boff + n * 2048 + k * 1024); } while (0)
; #define PG8_MMA(ai, bj, At, Bt) do { __builtin_amdgcn_s_setprio(1); _Pragma("unroll") for (int m = 0; m < 4; ++m) _Pragma("unroll") for (int n = 0; n < 2; ++n) _Pragma("unroll") for (int k = 0; k < 2; ++k) \
;         acc[ai][bj][m][n] = __builtin_amdgcn_mfma_f32_16x16x32_bf16(Bt[n][k], At[m][k], acc[ai][bj][m][n], 0, 0, 0); __builtin_amdgcn_s_setprio(0); } while (0)
; #define PG8_WAIT_V(n) asm volatile("s_waitcnt vmcnt(" #n ")" ::: "memory")
; #define PG8_WAIT_L(n) asm volatile("s_waitcnt lgkmcnt(" #n ")" ::: "memory")
; #define PG8_BAR __builtin_amdgcn_s_barrier()
; #define PG8_SCHED __builtin_amdgcn_sched_barrier(0)
; template <class Epi, class Sched, bool ALIGN_EPI = false, bool SP2 = false>
; __device__ __forceinline__ void gemm_phase(PG8_LAS unsigned char* lds, const Gemm g, const Sched& S, const Epi& E, const int tid) {
;     ...
;             PG8_WAIT_V(8); PG8_WAIT_L(0); PG8_BAR; PG8_MMA(1, 0, At, B0); PG8_MMA(1, 1, At, B1); PG8_BAR; PG8_SCHED;
;             PG8_LDB(B0, 1, 0); PG8_LDB(B1, 1, 1); PG8_SCHED; PG8_LDA(At, 1, 0); PG8_STAGE(PG8_SA(0, 1), a2 + hstepA, voffA);
;             PG8_WAIT_V(8); PG8_WAIT_L(0); PG8_BAR; PG8_MMA(0, 0, At, B0); PG8_MMA(0, 1, At, B1); PG8_BAR; PG8_SCHED;
;             PG8_LDA(At, 1, 1); PG8_STAGE(PG8_SB(1, 0), b3, voffB); PG8_STAGE(PG8_SB(1, 1), b3 + hstepB, voffB); PG8_STAGE(PG8_SA(1, 0), a3, voffA);
;             PG8_WAIT_V(8); PG8_WAIT_L(0); PG8_BAR; PG8_MMA(1, 0, At, B0); PG8_MMA(1, 1, At, B1); PG8_BAR; PG8_SCHED;
	s_add_i32 s55, 0, 0x18000
	s_add_i32 s56, 0, 0x1c000
	v_add_u32_e32 v10, s55, v140
	v_add_u32_e32 v11, s56, v140
	ds_read_b128 v[32:35], v10
	ds_read_b128 v[36:39], v10 offset:1024
	ds_read_b128 v[142:145], v10 offset:2048
	ds_read_b128 v[146:149], v10 offset:3072
	ds_read_b128 v[150:153], v11
	ds_read_b128 v[178:181], v11 offset:1024
	ds_read_b128 v[182:185], v11 offset:2048
	ds_read_b128 v[186:189], v11 offset:3072
	s_add_u32 s58, s18, 0x18100
	s_addc_u32 s59, s19, 0
	s_mov_b32 m0, s30
	v_lshl_add_u64 v[40:41], s[58:59], 0, v[134:135]
	ds_read_b128 v[190:193], v141 offset:32768
	ds_read_b128 v[194:197], v141 offset:33792
	ds_read_b128 v[198:201], v141 offset:34816
	ds_read_b128 v[218:221], v141 offset:35840
	ds_read_b128 v[222:225], v141 offset:36864
	ds_read_b128 v[226:229], v141 offset:37888
	ds_read_b128 v[238:241], v141 offset:38912
	ds_read_b128 v[242:245], v141 offset:39936
	global_load_lds_dwordx4 v[40:41], off nt
	v_lshl_add_u64 v[40:41], s[58:59], 0, v[130:131]
	s_mov_b32 m0, s31
	s_nop 0
	global_load_lds_dwordx4 v[40:41], off nt
	s_waitcnt vmcnt(8)
	s_waitcnt lgkmcnt(0)
	s_barrier
	s_setprio 1
	s_waitcnt lgkmcnt(0)
	v_mfma_f32_16x16x32_bf16 v[66:69], v[32:35], v[190:193], v[66:69]
	v_mfma_f32_16x16x32_bf16 v[70:73], v[142:145], v[190:193], v[70:73]
	v_mfma_f32_16x16x32_bf16 v[74:77], v[32:35], v[198:201], v[74:77]
	v_mfma_f32_16x16x32_bf16 v[78:81], v[142:145], v[198:201], v[78:81]
	v_mfma_f32_16x16x32_bf16 v[82:85], v[32:35], v[222:225], v[82:85]
	v_mfma_f32_16x16x32_bf16 v[86:89], v[142:145], v[222:225], v[86:89]
	v_mfma_f32_16x16x32_bf16 v[90:93], v[32:35], v[238:241], v[90:93]
	v_mfma_f32_16x16x32_bf16 v[94:97], v[142:145], v[238:241], v[94:97]
	v_mfma_f32_16x16x32_bf16 v[66:69], v[36:39], v[194:197], v[66:69]
	v_mfma_f32_16x16x32_bf16 v[70:73], v[146:149], v[194:197], v[70:73]
	v_mfma_f32_16x16x32_bf16 v[74:77], v[36:39], v[218:221], v[74:77]
	v_mfma_f32_16x16x32_bf16 v[78:81], v[146:149], v[218:221], v[78:81]
	v_mfma_f32_16x16x32_bf16 v[82:85], v[36:39], v[226:229], v[82:85]
	v_mfma_f32_16x16x32_bf16 v[86:89], v[146:149], v[226:229], v[86:89]
	v_mfma_f32_16x16x32_bf16 v[90:93], v[36:39], v[242:245], v[90:93]
	v_mfma_f32_16x16x32_bf16 v[94:97], v[146:149], v[242:245], v[94:97]
	s_setprio 0
	s_setprio 1
	v_mfma_f32_16x16x32_bf16 v[98:101], v[150:153], v[190:193], v[98:101]
	v_mfma_f32_16x16x32_bf16 v[102:105], v[182:185], v[190:193], v[102:105]
	v_mfma_f32_16x16x32_bf16 v[106:109], v[150:153], v[198:201], v[106:109]
	v_mfma_f32_16x16x32_bf16 v[40:43], v[182:185], v[198:201], v[42:45]
	v_mfma_f32_16x16x32_bf16 v[44:47], v[150:153], v[222:225], v[46:49]
	v_mfma_f32_16x16x32_bf16 v[48:51], v[182:185], v[222:225], v[50:53]
	v_mfma_f32_16x16x32_bf16 v[52:55], v[150:153], v[238:241], v[54:57]
	v_mfma_f32_16x16x32_bf16 v[56:59], v[182:185], v[238:241], v[58:61]
	v_mfma_f32_16x16x32_bf16 v[98:101], v[178:181], v[194:197], v[98:101]
	v_mfma_f32_16x16x32_bf16 v[102:105], v[186:189], v[194:197], v[102:105]
	v_mfma_f32_16x16x32_bf16 v[106:109], v[178:181], v[218:221], v[106:109]
	v_mfma_f32_16x16x32_bf16 v[40:43], v[186:189], v[218:221], v[40:43]
	v_mfma_f32_16x16x32_bf16 v[44:47], v[178:181], v[226:229], v[44:47]
	v_mfma_f32_16x16x32_bf16 v[48:51], v[186:189], v[226:229], v[48:51]
	v_mfma_f32_16x16x32_bf16 v[52:55], v[178:181], v[242:245], v[52:55]
	v_mfma_f32_16x16x32_bf16 v[56:59], v[186:189], v[242:245], v[56:59]
	s_setprio 0
	s_barrier
	s_add_i32 s59, s55, s27
	s_add_i32 s55, s59, 0x2000
	v_lshl_add_u64 v[60:61], v[0:1], 0, s[94:95]
	s_mov_b32 m0, s59
	s_add_u32 s60, s20, 0x18180
	ds_read_b128 v[190:193], v141 offset:49152
	ds_read_b128 v[194:197], v141 offset:50176
	ds_read_b128 v[198:201], v141 offset:51200
	ds_read_b128 v[218:221], v141 offset:52224
	ds_read_b128 v[222:225], v141 offset:53248
	ds_read_b128 v[226:229], v141 offset:54272
	ds_read_b128 v[238:241], v141 offset:55296
	ds_read_b128 v[242:245], v141 offset:56320
	global_load_lds_dwordx4 v[60:61], off
	v_lshl_add_u64 v[60:61], v[2:3], 0, s[94:95]
	s_mov_b32 m0, s55
	s_addc_u32 s61, s21, 0
	s_add_i32 s56, s56, s27
	global_load_lds_dwordx4 v[60:61], off
	v_lshl_add_u64 v[60:61], s[60:61], 0, v[132:133]
	s_mov_b32 m0, s56
	s_add_i32 s58, s56, 0x2000
	global_load_lds_dwordx4 v[60:61], off
	v_lshl_add_u64 v[60:61], s[60:61], 0, v[128:129]
	s_mov_b32 m0, s58
	s_nop 0
	global_load_lds_dwordx4 v[60:61], off
	v_lshl_add_u64 v[60:61], v[4:5], 0, s[94:95]
	s_mov_b32 m0, s35
	s_nop 0
	global_load_lds_dwordx4 v[60:61], off nt
	v_lshl_add_u64 v[60:61], v[6:7], 0, s[94:95]
	s_mov_b32 m0, s36
	s_nop 0
	global_load_lds_dwordx4 v[60:61], off nt
	s_waitcnt vmcnt(8)
	s_waitcnt lgkmcnt(0)
	s_barrier
; #define PG8_STAGE(bufoff, gbase, voff) do { _Pragma("unroll") for (int _i = 0; _i < 2; ++_i) \
;         __builtin_amdgcn_global_load_lds((const unsigned*)((const char*)(gbase) + (voff)[_i]), (PG8_LAS unsigned*)(lds + (bufoff) + ldsw + _i * 8192), 16, 0, 0); } while (0)
; #define PG8_LDA(dst, b, h) do { _Pragma("unroll") for (int m = 0; m < 4; ++m) _Pragma("unroll") for (int k = 0; k < 2; ++k) dst[m][k] = *(const PG8_LAS bf16x8*)(lds + PG8_SA(b, h) + aoff + m * 2048 + k * 1024); } while (0)
; #define PG8_MMA(ai, bj, At, Bt) do { __builtin_amdgcn_s_setprio(1); _Pragma("unroll") for (int m = 0; m < 4; ++m) _Pragma("unroll") for (int n = 0; n < 2; ++n) _Pragma("unroll") for (int k = 0; k < 2; ++k) \
;         acc[ai][bj][m][n] = __builtin_amdgcn_mfma_f32_16x16x32_bf16(Bt[n][k], At[m][k], acc[ai][bj][m][n], 0, 0, 0); __builtin_amdgcn_s_setprio(0); } while (0)
; #define PG8_WAIT_V(n) asm volatile("s_waitcnt vmcnt(" #n ")" ::: "memory")
; #define PG8_WAIT_L(n) asm volatile("s_waitcnt lgkmcnt(" #n ")" ::: "memory")
; #define PG8_BAR __builtin_amdgcn_s_barrier()
; #define PG8_SCHED __builtin_amdgcn_sched_barrier(0)
; template <class Epi, class Sched, bool ALIGN_EPI = false, bool SP2 = false>
; __device__ __forceinline__ void gemm_phase(PG8_LAS unsigned char* lds, const Gemm g, const Sched& S, const Epi& E, const int tid) {
;     ...
;             PG8_WAIT_V(8); PG8_WAIT_L(0); PG8_BAR; PG8_MMA(0, 0, At, B0); PG8_MMA(0, 1, At, B1); PG8_BAR; PG8_SCHED;
;             PG8_LDA(At, 1, 1); PG8_STAGE(PG8_SB(1, 0), b3, voffB); PG8_STAGE(PG8_SB(1, 1), b3 + hstepB, voffB); PG8_STAGE(PG8_SA(1, 0), a3, voffA);
;             PG8_WAIT_V(8); PG8_WAIT_L(0); PG8_BAR; PG8_MMA(1, 0, At, B0); PG8_MMA(1, 1, At, B1); PG8_BAR; PG8_SCHED;
	s_setprio 1
	s_waitcnt lgkmcnt(0)
	v_mfma_f32_16x16x32_bf16 v[12:15], v[32:35], v[238:241], v[12:15]
	v_mfma_f32_16x16x32_bf16 v[16:19], v[142:145], v[238:241], v[16:19]
	v_mfma_f32_16x16x32_bf16 v[154:157], v[32:35], v[190:193], v[154:157]
	v_mfma_f32_16x16x32_bf16 v[158:161], v[142:145], v[190:193], v[158:161]
	v_mfma_f32_16x16x32_bf16 v[162:165], v[32:35], v[198:201], v[162:165]
	v_mfma_f32_16x16x32_bf16 v[166:169], v[142:145], v[198:201], v[166:169]
	v_mfma_f32_16x16x32_bf16 v[170:173], v[32:35], v[222:225], v[170:173]
	v_mfma_f32_16x16x32_bf16 v[174:177], v[142:145], v[222:225], v[174:177]
	v_mfma_f32_16x16x32_bf16 v[12:15], v[36:39], v[242:245], v[12:15]
	v_mfma_f32_16x16x32_bf16 v[16:19], v[146:149], v[242:245], v[16:19]
	v_mfma_f32_16x16x32_bf16 v[154:157], v[36:39], v[194:197], v[154:157]
	v_mfma_f32_16x16x32_bf16 v[158:161], v[146:149], v[194:197], v[158:161]
	v_mfma_f32_16x16x32_bf16 v[162:165], v[36:39], v[218:221], v[162:165]
	v_mfma_f32_16x16x32_bf16 v[166:169], v[146:149], v[218:221], v[166:169]
	v_mfma_f32_16x16x32_bf16 v[170:173], v[36:39], v[226:229], v[170:173]
	v_mfma_f32_16x16x32_bf16 v[174:177], v[146:149], v[226:229], v[174:177]
	s_setprio 0
	s_setprio 1
	v_mfma_f32_16x16x32_bf16 v[20:23], v[150:153], v[190:193], v[20:23]
	v_mfma_f32_16x16x32_bf16 v[32:35], v[182:185], v[190:193], v[62:65]
	v_mfma_f32_16x16x32_bf16 v[36:39], v[150:153], v[198:201], v[110:113]
	v_mfma_f32_16x16x32_bf16 v[60:63], v[182:185], v[198:201], v[114:117]
	v_mfma_f32_16x16x32_bf16 v[110:113], v[150:153], v[222:225], v[118:121]
	v_mfma_f32_16x16x32_bf16 v[114:117], v[182:185], v[222:225], v[122:125]
	v_mfma_f32_16x16x32_bf16 v[24:27], v[150:153], v[238:241], v[24:27]
	v_mfma_f32_16x16x32_bf16 v[28:31], v[182:185], v[238:241], v[28:31]
	v_mfma_f32_16x16x32_bf16 v[20:23], v[178:181], v[194:197], v[20:23]
	v_mfma_f32_16x16x32_bf16 v[32:35], v[186:189], v[194:197], v[32:35]
	v_mfma_f32_16x16x32_bf16 v[36:39], v[178:181], v[218:221], v[36:39]
	v_mfma_f32_16x16x32_bf16 v[60:63], v[186:189], v[218:221], v[60:63]
	v_mfma_f32_16x16x32_bf16 v[110:113], v[178:181], v[226:229], v[110:113]
	v_mfma_f32_16x16x32_bf16 v[114:117], v[186:189], v[226:229], v[114:117]
	v_mfma_f32_16x16x32_bf16 v[24:27], v[178:181], v[242:245], v[24:27]
	v_mfma_f32_16x16x32_bf16 v[28:31], v[186:189], v[242:245], v[28:31]
	s_setprio 0
	s_barrier
	ds_read_b128 v[118:121], v8
	ds_read_b128 v[122:125], v8 offset:1024
	ds_read_b128 v[142:145], v8 offset:2048
	ds_read_b128 v[146:149], v8 offset:3072
	ds_read_b128 v[150:153], v9
	ds_read_b128 v[178:181], v9 offset:1024
	ds_read_b128 v[182:185], v9 offset:2048
	ds_read_b128 v[186:189], v9 offset:3072
	s_add_u32 s60, s18, 0x18180
	s_addc_u32 s61, s19, 0
	s_mov_b32 m0, s57
	v_lshl_add_u64 v[64:65], s[60:61], 0, v[134:135]
	ds_read_b128 v[190:193], v141
	ds_read_b128 v[194:197], v141 offset:1024
	ds_read_b128 v[198:201], v141 offset:2048
	ds_read_b128 v[218:221], v141 offset:3072
	ds_read_b128 v[222:225], v141 offset:4096
	ds_read_b128 v[226:229], v141 offset:5120
	ds_read_b128 v[238:241], v141 offset:6144
	ds_read_b128 v[242:245], v141 offset:7168
	global_load_lds_dwordx4 v[64:65], off nt
	v_lshl_add_u64 v[64:65], s[60:61], 0, v[130:131]
	s_mov_b32 m0, s43
	s_nop 0
	global_load_lds_dwordx4 v[64:65], off nt
	s_waitcnt vmcnt(8)
	s_waitcnt lgkmcnt(0)
	s_barrier
	s_setprio 1
	s_waitcnt lgkmcnt(0)
	v_mfma_f32_16x16x32_bf16 v[64:67], v[118:121], v[190:193], v[66:69]
	v_mfma_f32_16x16x32_bf16 v[68:71], v[142:145], v[190:193], v[70:73]
	v_mfma_f32_16x16x32_bf16 v[72:75], v[118:121], v[198:201], v[74:77]
	v_mfma_f32_16x16x32_bf16 v[76:79], v[142:145], v[198:201], v[78:81]
	v_mfma_f32_16x16x32_bf16 v[80:83], v[118:121], v[222:225], v[82:85]
	v_mfma_f32_16x16x32_bf16 v[84:87], v[142:145], v[222:225], v[86:89]
	v_mfma_f32_16x16x32_bf16 v[88:91], v[118:121], v[238:241], v[90:93]
	v_mfma_f32_16x16x32_bf16 v[92:95], v[142:145], v[238:241], v[94:97]
	v_mfma_f32_16x16x32_bf16 v[64:67], v[122:125], v[194:197], v[64:67]
	v_mfma_f32_16x16x32_bf16 v[68:71], v[146:149], v[194:197], v[68:71]
	v_mfma_f32_16x16x32_bf16 v[72:75], v[122:125], v[218:221], v[72:75]
	v_mfma_f32_16x16x32_bf16 v[76:79], v[146:149], v[218:221], v[76:79]
	v_mfma_f32_16x16x32_bf16 v[80:83], v[122:125], v[226:229], v[80:83]
	v_mfma_f32_16x16x32_bf16 v[84:87], v[146:149], v[226:229], v[84:87]
	v_mfma_f32_16x16x32_bf16 v[88:91], v[122:125], v[242:245], v[88:91]
	v_mfma_f32_16x16x32_bf16 v[92:95], v[146:149], v[242:245], v[92:95]
	s_setprio 0
	s_setprio 1
	v_mfma_f32_16x16x32_bf16 v[96:99], v[150:153], v[190:193], v[98:101]
	v_mfma_f32_16x16x32_bf16 v[100:103], v[182:185], v[190:193], v[102:105]
	v_mfma_f32_16x16x32_bf16 v[104:107], v[150:153], v[198:201], v[106:109]
	v_mfma_f32_16x16x32_bf16 v[40:43], v[182:185], v[198:201], v[40:43]
	v_mfma_f32_16x16x32_bf16 v[44:47], v[150:153], v[222:225], v[44:47]
	v_mfma_f32_16x16x32_bf16 v[48:51], v[182:185], v[222:225], v[48:51]
	v_mfma_f32_16x16x32_bf16 v[52:55], v[150:153], v[238:241], v[52:55]
	v_mfma_f32_16x16x32_bf16 v[56:59], v[182:185], v[238:241], v[56:59]
	v_mfma_f32_16x16x32_bf16 v[96:99], v[178:181], v[194:197], v[96:99]
	v_mfma_f32_16x16x32_bf16 v[100:103], v[186:189], v[194:197], v[100:103]
	v_mfma_f32_16x16x32_bf16 v[104:107], v[178:181], v[218:221], v[104:107]
	v_mfma_f32_16x16x32_bf16 v[40:43], v[186:189], v[218:221], v[40:43]
	v_mfma_f32_16x16x32_bf16 v[44:47], v[178:181], v[226:229], v[44:47]
	v_mfma_f32_16x16x32_bf16 v[48:51], v[186:189], v[226:229], v[48:51]
	v_mfma_f32_16x16x32_bf16 v[52:55], v[178:181], v[242:245], v[52:55]
	v_mfma_f32_16x16x32_bf16 v[56:59], v[186:189], v[242:245], v[56:59]
	s_setprio 0
	s_barrier
; #define PG8_STAGE(bufoff, gbase, voff) do { _Pragma("unroll") for (int _i = 0; _i < 2; ++_i) \
;         __builtin_amdgcn_global_load_lds((const unsigned*)((const char*)(gbase) + (voff)[_i]), (PG8_LAS unsigned*)(lds + (bufoff) + ldsw + _i * 8192), 16, 0, 0); } while (0)
; #define PG8_LDA(dst, b, h) do { _Pragma("unroll") for (int m = 0; m < 4; ++m) _Pragma("unroll") for (int k = 0; k < 2; ++k) dst[m][k] = *(const PG8_LAS bf16x8*)(lds + PG8_SA(b, h) + aoff + m * 2048 + k * 1024); } while (0)
; #define PG8_LDB(dst, b, h) do { _Pragma("unroll") for (int n = 0; n < 2; ++n) _Pragma("unroll") for (int k = 0; k < 2; ++k) dst[n][k] = *(const PG8_LAS bf16x8*)(lds + PG8_SB(b, h) + boff + n * 2048 + k * 1024); } while (0)
; #define PG8_MMA(ai, bj, At, Bt) do { __builtin_amdgcn_s_setprio(1); _Pragma("unroll") for (int m = 0; m < 4; ++m) _Pragma("unroll") for (int n = 0; n < 2; ++n) _Pragma("unroll") for (int k = 0; k < 2; ++k) \
;         acc[ai][bj][m][n] = __builtin_amdgcn_mfma_f32_16x16x32_bf16(Bt[n][k], At[m][k], acc[ai][bj][m][n], 0, 0, 0); __builtin_amdgcn_s_setprio(0); } while (0)
; #define PG8_WAIT_V(n) asm volatile("s_waitcnt vmcnt(" #n ")" ::: "memory")
; #define PG8_WAIT_L(n) asm volatile("s_waitcnt lgkmcnt(" #n ")" ::: "memory")
; #define PG8_BAR __builtin_amdgcn_s_barrier()
; #define PG8_SCHED __builtin_amdgcn_sched_barrier(0)
; template <class Epi, class Sched, bool ALIGN_EPI = false, bool SP2 = false>
; __device__ __forceinline__ void gemm_phase(PG8_LAS unsigned char* lds, const Gemm g, const Sched& S, const Epi& E, const int tid) {
;     ...
;             PG8_LDA(At, 0, 1); PG8_STAGE(PG8_SB(0, 0), b2, voffB); PG8_STAGE(PG8_SB(0, 1), b2 + hstepB, voffB); PG8_STAGE(PG8_SA(0, 0), a2, voffA);
;             PG8_WAIT_V(8); PG8_WAIT_L(0); PG8_BAR; PG8_MMA(1, 0, At, B0); PG8_MMA(1, 1, At, B1); PG8_BAR; PG8_SCHED;
;             PG8_LDB(B0, 1, 0); PG8_LDB(B1, 1, 1); PG8_SCHED; PG8_LDA(At, 1, 0); PG8_STAGE(PG8_SA(0, 1), a2 + hstepA, voffA);
;             PG8_WAIT_V(8); PG8_WAIT_L(0); PG8_BAR; PG8_MMA(0, 0, At, B0); PG8_MMA(0, 1, At, B1); PG8_BAR; PG8_SCHED;
	s_mov_b32 m0, s54
	v_lshl_add_u64 v[108:109], v[0:1], 0, s[92:93]
	s_add_u32 s60, s20, 0x18200
	ds_read_b128 v[190:193], v141 offset:16384
	ds_read_b128 v[194:197], v141 offset:17408
	ds_read_b128 v[198:201], v141 offset:18432
	ds_read_b128 v[218:221], v141 offset:19456
	ds_read_b128 v[222:225], v141 offset:20480
	ds_read_b128 v[226:229], v141 offset:21504
	ds_read_b128 v[238:241], v141 offset:22528
	ds_read_b128 v[242:245], v141 offset:23552
	global_load_lds_dwordx4 v[108:109], off
	v_lshl_add_u64 v[108:109], v[2:3], 0, s[92:93]
	s_mov_b32 m0, s47
	s_addc_u32 s61, s21, 0
	global_load_lds_dwordx4 v[108:109], off
	v_lshl_add_u64 v[108:109], s[60:61], 0, v[132:133]
	s_mov_b32 m0, s49
	s_nop 0
	global_load_lds_dwordx4 v[108:109], off
	v_lshl_add_u64 v[108:109], s[60:61], 0, v[128:129]
	s_mov_b32 m0, s50
	s_nop 0
	global_load_lds_dwordx4 v[108:109], off
	v_lshl_add_u64 v[108:109], v[4:5], 0, s[92:93]
	s_mov_b32 m0, s28
	s_nop 0
	global_load_lds_dwordx4 v[108:109], off nt
	v_lshl_add_u64 v[108:109], v[6:7], 0, s[92:93]
	s_mov_b32 m0, s29
	s_nop 0
	global_load_lds_dwordx4 v[108:109], off nt
	s_waitcnt vmcnt(8)
	s_waitcnt lgkmcnt(0)
	s_barrier
	s_setprio 1
	s_waitcnt lgkmcnt(0)
	v_mfma_f32_16x16x32_bf16 v[12:15], v[118:121], v[238:241], v[12:15]
	v_mfma_f32_16x16x32_bf16 v[16:19], v[142:145], v[238:241], v[16:19]
	v_mfma_f32_16x16x32_bf16 v[154:157], v[118:121], v[190:193], v[154:157]
	v_mfma_f32_16x16x32_bf16 v[158:161], v[142:145], v[190:193], v[158:161]
	v_mfma_f32_16x16x32_bf16 v[162:165], v[118:121], v[198:201], v[162:165]
	v_mfma_f32_16x16x32_bf16 v[166:169], v[142:145], v[198:201], v[166:169]
	v_mfma_f32_16x16x32_bf16 v[170:173], v[118:121], v[222:225], v[170:173]
	v_mfma_f32_16x16x32_bf16 v[174:177], v[142:145], v[222:225], v[174:177]
	v_mfma_f32_16x16x32_bf16 v[12:15], v[122:125], v[242:245], v[12:15]
	v_mfma_f32_16x16x32_bf16 v[16:19], v[146:149], v[242:245], v[16:19]
	v_mfma_f32_16x16x32_bf16 v[154:157], v[122:125], v[194:197], v[154:157]
	v_mfma_f32_16x16x32_bf16 v[158:161], v[146:149], v[194:197], v[158:161]
	v_mfma_f32_16x16x32_bf16 v[162:165], v[122:125], v[218:221], v[162:165]
	v_mfma_f32_16x16x32_bf16 v[166:169], v[146:149], v[218:221], v[166:169]
	v_mfma_f32_16x16x32_bf16 v[170:173], v[122:125], v[226:229], v[170:173]
	v_mfma_f32_16x16x32_bf16 v[174:177], v[146:149], v[226:229], v[174:177]
	s_setprio 0
	s_setprio 1
	v_mfma_f32_16x16x32_bf16 v[20:23], v[150:153], v[190:193], v[20:23]
	v_mfma_f32_16x16x32_bf16 v[32:35], v[182:185], v[190:193], v[32:35]
	v_mfma_f32_16x16x32_bf16 v[36:39], v[150:153], v[198:201], v[36:39]
	v_mfma_f32_16x16x32_bf16 v[60:63], v[182:185], v[198:201], v[60:63]
	v_mfma_f32_16x16x32_bf16 v[108:111], v[150:153], v[222:225], v[110:113]
	v_mfma_f32_16x16x32_bf16 v[112:115], v[182:185], v[222:225], v[114:117]
	v_mfma_f32_16x16x32_bf16 v[24:27], v[150:153], v[238:241], v[24:27]
	v_mfma_f32_16x16x32_bf16 v[28:31], v[182:185], v[238:241], v[28:31]
	v_mfma_f32_16x16x32_bf16 v[20:23], v[178:181], v[194:197], v[20:23]
	v_mfma_f32_16x16x32_bf16 v[32:35], v[186:189], v[194:197], v[32:35]
	v_mfma_f32_16x16x32_bf16 v[36:39], v[178:181], v[218:221], v[36:39]
	v_mfma_f32_16x16x32_bf16 v[60:63], v[186:189], v[218:221], v[60:63]
	v_mfma_f32_16x16x32_bf16 v[108:111], v[178:181], v[226:229], v[108:111]
	v_mfma_f32_16x16x32_bf16 v[112:115], v[186:189], v[226:229], v[112:115]
	v_mfma_f32_16x16x32_bf16 v[24:27], v[178:181], v[242:245], v[24:27]
	v_mfma_f32_16x16x32_bf16 v[28:31], v[186:189], v[242:245], v[28:31]
	s_setprio 0
	s_barrier
	ds_read_b128 v[116:119], v10
	ds_read_b128 v[120:123], v10 offset:1024
	ds_read_b128 v[124:127], v10 offset:2048
	ds_read_b128 v[142:145], v10 offset:3072
	ds_read_b128 v[146:149], v11
	ds_read_b128 v[150:153], v11 offset:1024
	ds_read_b128 v[178:181], v11 offset:2048
	ds_read_b128 v[182:185], v11 offset:3072
	s_add_u32 s60, s18, 0x18200
	s_addc_u32 s61, s19, 0
	s_mov_b32 m0, s30
	v_lshl_add_u64 v[136:137], s[60:61], 0, v[134:135]
	ds_read_b128 v[186:189], v141 offset:32768
	ds_read_b128 v[190:193], v141 offset:33792
	ds_read_b128 v[194:197], v141 offset:34816
	ds_read_b128 v[198:201], v141 offset:35840
	ds_read_b128 v[218:221], v141 offset:36864
	ds_read_b128 v[222:225], v141 offset:37888
	ds_read_b128 v[226:229], v141 offset:38912
	ds_read_b128 v[238:241], v141 offset:39936
	global_load_lds_dwordx4 v[136:137], off nt
	v_lshl_add_u64 v[136:137], s[60:61], 0, v[130:131]
	s_mov_b32 m0, s31
	s_nop 0
	global_load_lds_dwordx4 v[136:137], off nt
	s_waitcnt vmcnt(8)
	s_waitcnt lgkmcnt(0)
	s_barrier
; #define PG8_STAGE(bufoff, gbase, voff) do { _Pragma("unroll") for (int _i = 0; _i < 2; ++_i) \
;         __builtin_amdgcn_global_load_lds((const unsigned*)((const char*)(gbase) + (voff)[_i]), (PG8_LAS unsigned*)(lds + (bufoff) + ldsw + _i * 8192), 16, 0, 0); } while (0)
; #define PG8_LDA(dst, b, h) do { _Pragma("unroll") for (int m = 0; m < 4; ++m) _Pragma("unroll") for (int k = 0; k < 2; ++k) dst[m][k] = *(const PG8_LAS bf16x8*)(lds + PG8_SA(b, h) + aoff + m * 2048 + k * 1024); } while (0)
; #define PG8_MMA(ai, bj, At, Bt) do { __builtin_amdgcn_s_setprio(1); _Pragma("unroll") for (int m = 0; m < 4; ++m) _Pragma("unroll") for (int n = 0; n < 2; ++n) _Pragma("unroll") for (int k = 0; k < 2; ++k) \
;         acc[ai][bj][m][n] = __builtin_amdgcn_mfma_f32_16x16x32_bf16(Bt[n][k], At[m][k], acc[ai][bj][m][n], 0, 0, 0); __builtin_amdgcn_s_setprio(0); } while (0)
; #define PG8_WAIT_V(n) asm volatile("s_waitcnt vmcnt(" #n ")" ::: "memory")
; #define PG8_WAIT_L(n) asm volatile("s_waitcnt lgkmcnt(" #n ")" ::: "memory")
; #define PG8_BAR __builtin_amdgcn_s_barrier()
; #define PG8_SCHED __builtin_amdgcn_sched_barrier(0)
; template <class Epi, class Sched, bool ALIGN_EPI = false, bool SP2 = false>
; __device__ __forceinline__ void gemm_phase(PG8_LAS unsigned char* lds, const Gemm g, const Sched& S, const Epi& E, const int tid) {
;     ...
;             PG8_WAIT_V(8); PG8_WAIT_L(0); PG8_BAR; PG8_MMA(0, 0, At, B0); PG8_MMA(0, 1, At, B1); PG8_BAR; PG8_SCHED;
;             PG8_LDA(At, 1, 1); PG8_STAGE(PG8_SB(1, 0), b3, voffB); PG8_STAGE(PG8_SB(1, 1), b3 + hstepB, voffB); PG8_STAGE(PG8_SA(1, 0), a3, voffA);
;             PG8_WAIT_V(8); PG8_WAIT_L(0); PG8_BAR; PG8_MMA(1, 0, At, B0); PG8_MMA(1, 1, At, B1); PG8_BAR; PG8_SCHED;
	s_setprio 1
	s_waitcnt lgkmcnt(0)
	v_mfma_f32_16x16x32_bf16 v[64:67], v[116:119], v[186:189], v[64:67]
	v_mfma_f32_16x16x32_bf16 v[68:71], v[124:127], v[186:189], v[68:71]
	v_mfma_f32_16x16x32_bf16 v[72:75], v[116:119], v[194:197], v[72:75]
	v_mfma_f32_16x16x32_bf16 v[76:79], v[124:127], v[194:197], v[76:79]
	v_mfma_f32_16x16x32_bf16 v[80:83], v[116:119], v[218:221], v[80:83]
	v_mfma_f32_16x16x32_bf16 v[84:87], v[124:127], v[218:221], v[84:87]
	v_mfma_f32_16x16x32_bf16 v[88:91], v[116:119], v[226:229], v[88:91]
	v_mfma_f32_16x16x32_bf16 v[92:95], v[124:127], v[226:229], v[92:95]
	v_mfma_f32_16x16x32_bf16 v[64:67], v[120:123], v[190:193], v[64:67]
	v_mfma_f32_16x16x32_bf16 v[68:71], v[142:145], v[190:193], v[68:71]
	v_mfma_f32_16x16x32_bf16 v[72:75], v[120:123], v[198:201], v[72:75]
	v_mfma_f32_16x16x32_bf16 v[76:79], v[142:145], v[198:201], v[76:79]
	v_mfma_f32_16x16x32_bf16 v[80:83], v[120:123], v[222:225], v[80:83]
	v_mfma_f32_16x16x32_bf16 v[84:87], v[142:145], v[222:225], v[84:87]
	v_mfma_f32_16x16x32_bf16 v[88:91], v[120:123], v[238:241], v[88:91]
	v_mfma_f32_16x16x32_bf16 v[92:95], v[142:145], v[238:241], v[92:95]
	s_setprio 0
	s_setprio 1
	v_mfma_f32_16x16x32_bf16 v[96:99], v[146:149], v[186:189], v[96:99]
	v_mfma_f32_16x16x32_bf16 v[100:103], v[178:181], v[186:189], v[100:103]
	v_mfma_f32_16x16x32_bf16 v[104:107], v[146:149], v[194:197], v[104:107]
	v_mfma_f32_16x16x32_bf16 v[40:43], v[178:181], v[194:197], v[40:43]
	v_mfma_f32_16x16x32_bf16 v[44:47], v[146:149], v[218:221], v[44:47]
	v_mfma_f32_16x16x32_bf16 v[48:51], v[178:181], v[218:221], v[48:51]
	v_mfma_f32_16x16x32_bf16 v[52:55], v[146:149], v[226:229], v[52:55]
	v_mfma_f32_16x16x32_bf16 v[56:59], v[178:181], v[226:229], v[56:59]
	v_mfma_f32_16x16x32_bf16 v[96:99], v[150:153], v[190:193], v[96:99]
	v_mfma_f32_16x16x32_bf16 v[100:103], v[182:185], v[190:193], v[100:103]
	v_mfma_f32_16x16x32_bf16 v[104:107], v[150:153], v[198:201], v[104:107]
	v_mfma_f32_16x16x32_bf16 v[40:43], v[182:185], v[198:201], v[40:43]
	v_mfma_f32_16x16x32_bf16 v[44:47], v[150:153], v[222:225], v[44:47]
	v_mfma_f32_16x16x32_bf16 v[48:51], v[182:185], v[222:225], v[48:51]
	v_mfma_f32_16x16x32_bf16 v[52:55], v[150:153], v[238:241], v[52:55]
	v_mfma_f32_16x16x32_bf16 v[56:59], v[182:185], v[238:241], v[56:59]
	s_setprio 0
	s_barrier
	s_mov_b32 m0, s59
	v_lshl_add_u64 v[0:1], v[0:1], 0, s[96:97]
	s_add_u32 s20, s20, 0x18280
	ds_read_b128 v[186:189], v141 offset:49152
	ds_read_b128 v[190:193], v141 offset:50176
	ds_read_b128 v[194:197], v141 offset:51200
	ds_read_b128 v[198:201], v141 offset:52224
	ds_read_b128 v[218:221], v141 offset:53248
	ds_read_b128 v[222:225], v141 offset:54272
	ds_read_b128 v[226:229], v141 offset:55296
	ds_read_b128 v[238:241], v141 offset:56320
	global_load_lds_dwordx4 v[0:1], off
	v_lshl_add_u64 v[0:1], v[2:3], 0, s[96:97]
	s_mov_b32 m0, s55
	s_addc_u32 s21, s21, 0
	global_load_lds_dwordx4 v[0:1], off
	v_lshl_add_u64 v[0:1], s[20:21], 0, v[132:133]
	s_mov_b32 m0, s56
	s_nop 0
	global_load_lds_dwordx4 v[0:1], off
	v_lshl_add_u64 v[0:1], s[20:21], 0, v[128:129]
	s_mov_b32 m0, s58
	s_nop 0
	global_load_lds_dwordx4 v[0:1], off
	v_lshl_add_u64 v[0:1], v[4:5], 0, s[96:97]
	s_mov_b32 m0, s35
	s_nop 0
	global_load_lds_dwordx4 v[0:1], off nt
	v_lshl_add_u64 v[0:1], v[6:7], 0, s[96:97]
	s_mov_b32 m0, s36
	s_nop 0
	global_load_lds_dwordx4 v[0:1], off nt
	s_waitcnt vmcnt(8)
	s_waitcnt lgkmcnt(0)
	s_barrier
	s_setprio 1
	s_waitcnt lgkmcnt(0)
	v_mfma_f32_16x16x32_bf16 v[0:3], v[116:119], v[186:189], v[154:157]
	v_mfma_f32_16x16x32_bf16 v[4:7], v[124:127], v[186:189], v[158:161]
	v_mfma_f32_16x16x32_bf16 v[12:15], v[116:119], v[226:229], v[12:15]
	v_mfma_f32_16x16x32_bf16 v[16:19], v[124:127], v[226:229], v[16:19]
	v_mfma_f32_16x16x32_bf16 v[0:3], v[120:123], v[190:193], v[0:3]
	v_mfma_f32_16x16x32_bf16 v[4:7], v[142:145], v[190:193], v[4:7]
	v_mfma_f32_16x16x32_bf16 v[154:157], v[116:119], v[194:197], v[162:165]
	v_mfma_f32_16x16x32_bf16 v[158:161], v[124:127], v[194:197], v[166:169]
	v_mfma_f32_16x16x32_bf16 v[162:165], v[116:119], v[218:221], v[170:173]
	v_mfma_f32_16x16x32_bf16 v[166:169], v[124:127], v[218:221], v[174:177]
	v_mfma_f32_16x16x32_bf16 v[12:15], v[120:123], v[238:241], v[12:15]
	v_mfma_f32_16x16x32_bf16 v[16:19], v[142:145], v[238:241], v[16:19]
	v_mfma_f32_16x16x32_bf16 v[154:157], v[120:123], v[198:201], v[154:157]
	v_mfma_f32_16x16x32_bf16 v[158:161], v[142:145], v[198:201], v[158:161]
	v_mfma_f32_16x16x32_bf16 v[162:165], v[120:123], v[222:225], v[162:165]
	v_mfma_f32_16x16x32_bf16 v[166:169], v[142:145], v[222:225], v[166:169]
	s_setprio 0
	s_setprio 1
	v_mfma_f32_16x16x32_bf16 v[20:23], v[146:149], v[186:189], v[20:23]
	v_mfma_f32_16x16x32_bf16 v[32:35], v[178:181], v[186:189], v[32:35]
	v_mfma_f32_16x16x32_bf16 v[36:39], v[146:149], v[194:197], v[36:39]
	v_mfma_f32_16x16x32_bf16 v[60:63], v[178:181], v[194:197], v[60:63]
	v_mfma_f32_16x16x32_bf16 v[108:111], v[146:149], v[218:221], v[108:111]
	v_mfma_f32_16x16x32_bf16 v[112:115], v[178:181], v[218:221], v[112:115]
	v_mfma_f32_16x16x32_bf16 v[24:27], v[146:149], v[226:229], v[24:27]
	v_mfma_f32_16x16x32_bf16 v[28:31], v[178:181], v[226:229], v[28:31]
	v_mfma_f32_16x16x32_bf16 v[20:23], v[150:153], v[190:193], v[20:23]
	v_mfma_f32_16x16x32_bf16 v[32:35], v[182:185], v[190:193], v[32:35]
	v_mfma_f32_16x16x32_bf16 v[36:39], v[150:153], v[198:201], v[36:39]
	v_mfma_f32_16x16x32_bf16 v[60:63], v[182:185], v[198:201], v[60:63]
	v_mfma_f32_16x16x32_bf16 v[108:111], v[150:153], v[222:225], v[108:111]
	v_mfma_f32_16x16x32_bf16 v[112:115], v[182:185], v[222:225], v[112:115]
	v_mfma_f32_16x16x32_bf16 v[24:27], v[150:153], v[238:241], v[24:27]
	v_mfma_f32_16x16x32_bf16 v[28:31], v[182:185], v[238:241], v[28:31]
	s_setprio 0
	s_barrier
; #define PG8_STAGE(bufoff, gbase, voff) do { _Pragma("unroll") for (int _i = 0; _i < 2; ++_i) \
;         __builtin_amdgcn_global_load_lds((const unsigned*)((const char*)(gbase) + (voff)[_i]), (PG8_LAS unsigned*)(lds + (bufoff) + ldsw + _i * 8192), 16, 0, 0); } while (0)
; #define PG8_LDA(dst, b, h) do { _Pragma("unroll") for (int m = 0; m < 4; ++m) _Pragma("unroll") for (int k = 0; k < 2; ++k) dst[m][k] = *(const PG8_LAS bf16x8*)(lds + PG8_SA(b, h) + aoff + m * 2048 + k * 1024); } while (0)
; #define PG8_LDB(dst, b, h) do { _Pragma("unroll") for (int n = 0; n < 2; ++n) _Pragma("unroll") for (int k = 0; k < 2; ++k) dst[n][k] = *(const PG8_LAS bf16x8*)(lds + PG8_SB(b, h) + boff + n * 2048 + k * 1024); } while (0)
; #define PG8_MMA(ai, bj, At, Bt) do { __builtin_amdgcn_s_setprio(1); _Pragma("unroll") for (int m = 0; m < 4; ++m) _Pragma("unroll") for (int n = 0; n < 2; ++n) _Pragma("unroll") for (int k = 0; k < 2; ++k) \
;         acc[ai][bj][m][n] = __builtin_amdgcn_mfma_f32_16x16x32_bf16(Bt[n][k], At[m][k], acc[ai][bj][m][n], 0, 0, 0); __builtin_amdgcn_s_setprio(0); } while (0)
; #define PG8_WAIT_V(n) asm volatile("s_waitcnt vmcnt(" #n ")" ::: "memory")
; #define PG8_WAIT_L(n) asm volatile("s_waitcnt lgkmcnt(" #n ")" ::: "memory")
; template <class Epi, class Sched, bool ALIGN_EPI = false, bool SP2 = false>
; __device__ __forceinline__ void gemm_phase(PG8_LAS unsigned char* lds, const Gemm g, const Sched& S, const Epi& E, const int tid) {
;     ...
;             const bool last = (t == nt - 2);
;             const char* a1 = cA + (size_t)(t + 1) * kstep;
;             const char* a2 = last ? nA : cA + (size_t)(t + 2) * kstep; const char* b2 = last ? nB : cB + (size_t)(t + 2) * kstep;
;             const char* a3 = a2 + kstep; const char* b3 = b2 + kstep;
;             if (last && has_next) S.a_ready(nxt);
;             if constexpr (SP2) {
;             PG8_LDB(B0, 0, 0); PG8_LDB(B1, 0, 1); PG8_SCHED; PG8_LDA(At, 0, 0); PG8_STAGE(PG8_SA(1, 1), a1 + hstepA, voffA);
;             PG8_WAIT_V(8); PG8_WAIT_L(0); PG8_BAR; PG8_MMA(0, 0, At, B0); PG8_MMA(0, 1, At, B1); PG8_BAR; PG8_SCHED;
;             PG8_LDA(At, 0, 1); PG8_STAGE(PG8_SB(0, 0), b2, voffB); PG8_STAGE(PG8_SB(0, 1), b2 + hstepB, voffB); PG8_STAGE(PG8_SA(0, 0), a2, voffA);
;             PG8_WAIT_V(8); PG8_WAIT_L(0); PG8_BAR; PG8_MMA(1, 0, At, B0); PG8_MMA(1, 1, At, B1); PG8_BAR; PG8_SCHED;
	ds_read_b128 v[116:119], v8
	ds_read_b128 v[120:123], v8 offset:1024
	ds_read_b128 v[124:127], v8 offset:2048
	ds_read_b128 v[142:145], v8 offset:3072
	ds_read_b128 v[146:149], v9
	ds_read_b128 v[150:153], v9 offset:1024
	ds_read_b128 v[170:173], v9 offset:2048
	ds_read_b128 v[174:177], v9 offset:3072
	s_add_u32 s18, s18, 0x18280
	s_addc_u32 s19, s19, 0
	s_mov_b32 m0, s57
	v_lshl_add_u64 v[8:9], s[18:19], 0, v[134:135]
	ds_read_b128 v[178:181], v141
	ds_read_b128 v[182:185], v141 offset:1024
	ds_read_b128 v[186:189], v141 offset:2048
	ds_read_b128 v[190:193], v141 offset:3072
	ds_read_b128 v[194:197], v141 offset:4096
	ds_read_b128 v[198:201], v141 offset:5120
	ds_read_b128 v[218:221], v141 offset:6144
	ds_read_b128 v[222:225], v141 offset:7168
	global_load_lds_dwordx4 v[8:9], off nt
	v_lshl_add_u64 v[8:9], s[18:19], 0, v[130:131]
	s_mov_b32 m0, s43
	s_nop 0
	global_load_lds_dwordx4 v[8:9], off nt
	s_waitcnt vmcnt(8)
	s_waitcnt lgkmcnt(0)
	s_barrier
	s_setprio 1
	s_waitcnt lgkmcnt(0)
	v_mfma_f32_16x16x32_bf16 v[64:67], v[116:119], v[178:181], v[64:67]
	v_mfma_f32_16x16x32_bf16 v[68:71], v[124:127], v[178:181], v[68:71]
	v_mfma_f32_16x16x32_bf16 v[72:75], v[116:119], v[186:189], v[72:75]
	v_mfma_f32_16x16x32_bf16 v[76:79], v[124:127], v[186:189], v[76:79]
	v_mfma_f32_16x16x32_bf16 v[80:83], v[116:119], v[194:197], v[80:83]
	v_mfma_f32_16x16x32_bf16 v[84:87], v[124:127], v[194:197], v[84:87]
	v_mfma_f32_16x16x32_bf16 v[88:91], v[116:119], v[218:221], v[88:91]
	v_mfma_f32_16x16x32_bf16 v[64:67], v[120:123], v[182:185], v[64:67]
	v_mfma_f32_16x16x32_bf16 v[68:71], v[142:145], v[182:185], v[68:71]
	v_mfma_f32_16x16x32_bf16 v[72:75], v[120:123], v[190:193], v[72:75]
	v_mfma_f32_16x16x32_bf16 v[76:79], v[142:145], v[190:193], v[76:79]
	v_mfma_f32_16x16x32_bf16 v[80:83], v[120:123], v[198:201], v[80:83]
	v_mfma_f32_16x16x32_bf16 v[84:87], v[142:145], v[198:201], v[84:87]
	v_mfma_f32_16x16x32_bf16 v[226:229], v[120:123], v[222:225], v[88:91]
	v_mfma_f32_16x16x32_bf16 v[88:91], v[124:127], v[218:221], v[92:95]
	v_mfma_f32_16x16x32_bf16 v[238:241], v[142:145], v[222:225], v[88:91]
	s_setprio 0
	s_setprio 1
	v_mfma_f32_16x16x32_bf16 v[88:91], v[146:149], v[178:181], v[96:99]
	v_mfma_f32_16x16x32_bf16 v[96:99], v[150:153], v[182:185], v[88:91]
	v_mfma_f32_16x16x32_bf16 v[88:91], v[170:173], v[178:181], v[100:103]
	v_mfma_f32_16x16x32_bf16 v[40:43], v[170:173], v[186:189], v[40:43]
	v_mfma_f32_16x16x32_bf16 v[44:47], v[146:149], v[194:197], v[44:47]
	v_mfma_f32_16x16x32_bf16 v[48:51], v[170:173], v[194:197], v[48:51]
	v_mfma_f32_16x16x32_bf16 v[52:55], v[146:149], v[218:221], v[52:55]
	v_mfma_f32_16x16x32_bf16 v[56:59], v[170:173], v[218:221], v[56:59]
	v_mfma_f32_16x16x32_bf16 v[100:103], v[174:177], v[182:185], v[88:91]
	v_mfma_f32_16x16x32_bf16 v[88:91], v[146:149], v[186:189], v[104:107]
	v_mfma_f32_16x16x32_bf16 v[40:43], v[174:177], v[190:193], v[40:43]
	v_mfma_f32_16x16x32_bf16 v[44:47], v[150:153], v[198:201], v[44:47]
	v_mfma_f32_16x16x32_bf16 v[48:51], v[174:177], v[198:201], v[48:51]
	v_mfma_f32_16x16x32_bf16 v[52:55], v[150:153], v[222:225], v[52:55]
	v_mfma_f32_16x16x32_bf16 v[56:59], v[174:177], v[222:225], v[56:59]
	v_mfma_f32_16x16x32_bf16 v[178:181], v[150:153], v[190:193], v[88:91]
	s_setprio 0
	s_barrier
	s_mov_b32 m0, s54
	v_lshl_add_u64 v[136:137], s[16:17], 0, v[132:133]
	s_add_u32 s18, s16, 0x18000
	ds_read_b128 v[88:91], v141 offset:16384
	ds_read_b128 v[92:95], v141 offset:17408
	ds_read_b128 v[104:107], v141 offset:18432
	ds_read_b128 v[182:185], v141 offset:19456
	ds_read_b128 v[186:189], v141 offset:20480
	ds_read_b128 v[190:193], v141 offset:21504
	ds_read_b128 v[194:197], v141 offset:22528
	ds_read_b128 v[198:201], v141 offset:23552
	global_load_lds_dwordx4 v[136:137], off
	v_lshl_add_u64 v[202:203], s[16:17], 0, v[128:129]
	s_mov_b32 m0, s47
	s_addc_u32 s19, s17, 0
	global_load_lds_dwordx4 v[202:203], off
	v_lshl_add_u64 v[8:9], s[18:19], 0, v[132:133]
	s_mov_b32 m0, s49
	v_lshl_add_u64 v[232:233], s[0:1], 0, v[134:135]
	global_load_lds_dwordx4 v[8:9], off
	v_lshl_add_u64 v[8:9], s[18:19], 0, v[128:129]
	s_mov_b32 m0, s50
	v_lshl_add_u64 v[210:211], s[0:1], 0, v[130:131]
	global_load_lds_dwordx4 v[8:9], off
	s_mov_b32 m0, s28
	s_nop 0
	global_load_lds_dwordx4 v[232:233], off nt
	s_mov_b32 m0, s29
	s_nop 0
	global_load_lds_dwordx4 v[210:211], off nt
	s_waitcnt vmcnt(8)
	s_waitcnt lgkmcnt(0)
	s_barrier
	s_setprio 1
	s_waitcnt lgkmcnt(0)
	v_mfma_f32_16x16x32_bf16 v[0:3], v[116:119], v[88:91], v[0:3]
	v_mfma_f32_16x16x32_bf16 v[4:7], v[124:127], v[88:91], v[4:7]
	v_mfma_f32_16x16x32_bf16 v[12:15], v[116:119], v[194:197], v[12:15]
	v_mfma_f32_16x16x32_bf16 v[16:19], v[124:127], v[194:197], v[16:19]
	v_mfma_f32_16x16x32_bf16 v[0:3], v[120:123], v[92:95], v[0:3]
	v_mfma_f32_16x16x32_bf16 v[4:7], v[142:145], v[92:95], v[4:7]
	v_mfma_f32_16x16x32_bf16 v[154:157], v[116:119], v[104:107], v[154:157]
	v_mfma_f32_16x16x32_bf16 v[158:161], v[124:127], v[104:107], v[158:161]
	v_mfma_f32_16x16x32_bf16 v[162:165], v[116:119], v[186:189], v[162:165]
	v_mfma_f32_16x16x32_bf16 v[166:169], v[124:127], v[186:189], v[166:169]
	v_mfma_f32_16x16x32_bf16 v[12:15], v[120:123], v[198:201], v[12:15]
	v_mfma_f32_16x16x32_bf16 v[16:19], v[142:145], v[198:201], v[16:19]
	v_mfma_f32_16x16x32_bf16 v[154:157], v[120:123], v[182:185], v[154:157]
	v_mfma_f32_16x16x32_bf16 v[158:161], v[142:145], v[182:185], v[158:161]
	v_mfma_f32_16x16x32_bf16 v[162:165], v[120:123], v[190:193], v[162:165]
	v_mfma_f32_16x16x32_bf16 v[166:169], v[142:145], v[190:193], v[166:169]
	s_setprio 0
	s_setprio 1
	v_mfma_f32_16x16x32_bf16 v[60:63], v[170:173], v[104:107], v[60:63]
	v_mfma_f32_16x16x32_bf16 v[20:23], v[146:149], v[88:91], v[20:23]
	v_mfma_f32_16x16x32_bf16 v[32:35], v[170:173], v[88:91], v[32:35]
	v_mfma_f32_16x16x32_bf16 v[36:39], v[146:149], v[104:107], v[36:39]
	v_mfma_f32_16x16x32_bf16 v[142:145], v[174:177], v[182:185], v[60:63]
	v_mfma_f32_16x16x32_bf16 v[60:63], v[146:149], v[186:189], v[108:111]
	v_mfma_f32_16x16x32_bf16 v[24:27], v[146:149], v[194:197], v[24:27]
	v_mfma_f32_16x16x32_bf16 v[20:23], v[150:153], v[92:95], v[20:23]
	v_mfma_f32_16x16x32_bf16 v[32:35], v[174:177], v[92:95], v[32:35]
	v_mfma_f32_16x16x32_bf16 v[36:39], v[150:153], v[182:185], v[36:39]
	v_mfma_f32_16x16x32_bf16 v[182:185], v[150:153], v[190:193], v[60:63]
	v_mfma_f32_16x16x32_bf16 v[60:63], v[170:173], v[186:189], v[112:115]
	v_mfma_f32_16x16x32_bf16 v[146:149], v[150:153], v[198:201], v[24:27]
	v_mfma_f32_16x16x32_bf16 v[24:27], v[170:173], v[194:197], v[28:31]
	v_mfma_f32_16x16x32_bf16 v[186:189], v[174:177], v[190:193], v[60:63]
	v_mfma_f32_16x16x32_bf16 v[150:153], v[174:177], v[198:201], v[24:27]
	s_setprio 0
	s_barrier
; #define PG8_STAGE(bufoff, gbase, voff) do { _Pragma("unroll") for (int _i = 0; _i < 2; ++_i) \
;         __builtin_amdgcn_global_load_lds((const unsigned*)((const char*)(gbase) + (voff)[_i]), (PG8_LAS unsigned*)(lds + (bufoff) + ldsw + _i * 8192), 16, 0, 0); } while (0)
; #define PG8_LDA(dst, b, h) do { _Pragma("unroll") for (int m = 0; m < 4; ++m) _Pragma("unroll") for (int k = 0; k < 2; ++k) dst[m][k] = *(const PG8_LAS bf16x8*)(lds + PG8_SA(b, h) + aoff + m * 2048 + k * 1024); } while (0)
; #define PG8_LDB(dst, b, h) do { _Pragma("unroll") for (int n = 0; n < 2; ++n) _Pragma("unroll") for (int k = 0; k < 2; ++k) dst[n][k] = *(const PG8_LAS bf16x8*)(lds + PG8_SB(b, h) + boff + n * 2048 + k * 1024); } while (0)
; #define PG8_MMA(ai, bj, At, Bt) do { __builtin_amdgcn_s_setprio(1); _Pragma("unroll") for (int m = 0; m < 4; ++m) _Pragma("unroll") for (int n = 0; n < 2; ++n) _Pragma("unroll") for (int k = 0; k < 2; ++k) \
;         acc[ai][bj][m][n] = __builtin_amdgcn_mfma_f32_16x16x32_bf16(Bt[n][k], At[m][k], acc[ai][bj][m][n], 0, 0, 0); __builtin_amdgcn_s_setprio(0); } while (0)
; #define PG8_WAIT_V(n) asm volatile("s_waitcnt vmcnt(" #n ")" ::: "memory")
; #define PG8_WAIT_L(n) asm volatile("s_waitcnt lgkmcnt(" #n ")" ::: "memory")
; #define PG8_BAR __builtin_amdgcn_s_barrier()
; #define PG8_SCHED __builtin_amdgcn_sched_barrier(0)
; template <class Epi, class Sched, bool ALIGN_EPI = false, bool SP2 = false>
; __device__ __forceinline__ void gemm_phase(PG8_LAS unsigned char* lds, const Gemm g, const Sched& S, const Epi& E, const int tid) {
;     ...
;             PG8_LDB(B0, 1, 0); PG8_LDB(B1, 1, 1); PG8_SCHED; PG8_LDA(At, 1, 0); PG8_STAGE(PG8_SA(0, 1), a2 + hstepA, voffA);
;             PG8_WAIT_V(8); PG8_WAIT_L(0); PG8_BAR; PG8_MMA(0, 0, At, B0); PG8_MMA(0, 1, At, B1); PG8_BAR; PG8_SCHED;
;             PG8_LDA(At, 1, 1); PG8_STAGE(PG8_SB(1, 0), b3, voffB); PG8_STAGE(PG8_SB(1, 1), b3 + hstepB, voffB); PG8_STAGE(PG8_SA(1, 0), a3, voffA);
;             PG8_WAIT_V(8); PG8_WAIT_L(0); PG8_BAR; PG8_MMA(1, 0, At, B0); PG8_MMA(1, 1, At, B1); PG8_BAR; PG8_SCHED;
;     ...
;         if constexpr (ALIGN_EPI) { if (wr == 0) PG8_BAR; }
	ds_read_b128 v[170:173], v10
	ds_read_b128 v[174:177], v10 offset:1024
	ds_read_b128 v[190:193], v10 offset:2048
	ds_read_b128 v[194:197], v10 offset:3072
	ds_read_b128 v[198:201], v11
	ds_read_b128 v[218:221], v11 offset:1024
	ds_read_b128 v[222:225], v11 offset:2048
	ds_read_b128 v[242:245], v11 offset:3072
	s_add_u32 s18, s0, 0x18000
	s_addc_u32 s19, s1, 0
	s_mov_b32 m0, s30
	v_lshl_add_u64 v[88:89], s[18:19], 0, v[134:135]
	ds_read_b128 v[8:11], v141 offset:32768
	ds_read_b128 v[24:27], v141 offset:33792
	ds_read_b128 v[28:31], v141 offset:34816
	ds_read_b128 v[60:63], v141 offset:35840
	ds_read_b128 v[246:249], v141 offset:36864
	ds_read_b128 v[250:253], v141 offset:37888
	ds_read_b128 v[206:209], v141 offset:38912
	ds_read_b128 v[214:217], v141 offset:39936
	global_load_lds_dwordx4 v[88:89], off nt
	v_lshl_add_u64 v[88:89], s[18:19], 0, v[130:131]
	s_mov_b32 m0, s31
	s_nop 0
	global_load_lds_dwordx4 v[88:89], off nt
	s_waitcnt vmcnt(8)
	s_waitcnt lgkmcnt(0)
	s_barrier
	s_setprio 1
	s_waitcnt lgkmcnt(0)
	v_mfma_f32_16x16x32_bf16 v[64:67], v[170:173], v[8:11], v[64:67]
	v_mfma_f32_16x16x32_bf16 v[124:127], v[174:177], v[24:27], v[64:67]
	v_mfma_f32_16x16x32_bf16 v[64:67], v[190:193], v[8:11], v[68:71]
	v_mfma_f32_16x16x32_bf16 v[120:123], v[194:197], v[24:27], v[64:67]
	v_mfma_f32_16x16x32_bf16 v[64:67], v[170:173], v[28:31], v[72:75]
	v_mfma_f32_16x16x32_bf16 v[108:111], v[174:177], v[60:63], v[64:67]
	v_mfma_f32_16x16x32_bf16 v[64:67], v[190:193], v[28:31], v[76:79]
	v_mfma_f32_16x16x32_bf16 v[104:107], v[194:197], v[60:63], v[64:67]
	v_mfma_f32_16x16x32_bf16 v[64:67], v[170:173], v[246:249], v[80:83]
	v_mfma_f32_16x16x32_bf16 v[92:95], v[174:177], v[250:253], v[64:67]
	v_mfma_f32_16x16x32_bf16 v[64:67], v[190:193], v[246:249], v[84:87]
	v_mfma_f32_16x16x32_bf16 v[88:91], v[194:197], v[250:253], v[64:67]
	v_mfma_f32_16x16x32_bf16 v[64:67], v[170:173], v[206:209], v[226:229]
	v_mfma_f32_16x16x32_bf16 v[76:79], v[174:177], v[214:217], v[64:67]
	v_mfma_f32_16x16x32_bf16 v[64:67], v[190:193], v[206:209], v[238:241]
	v_mfma_f32_16x16x32_bf16 v[72:75], v[194:197], v[214:217], v[64:67]
	s_setprio 0
	s_setprio 1
	v_mfma_f32_16x16x32_bf16 v[64:67], v[198:201], v[8:11], v[96:99]
	v_mfma_f32_16x16x32_bf16 v[8:11], v[222:225], v[8:11], v[100:103]
	v_mfma_f32_16x16x32_bf16 v[112:115], v[242:245], v[24:27], v[8:11]
	v_mfma_f32_16x16x32_bf16 v[8:11], v[198:201], v[28:31], v[178:181]
	v_mfma_f32_16x16x32_bf16 v[100:103], v[218:221], v[60:63], v[8:11]
	v_mfma_f32_16x16x32_bf16 v[8:11], v[222:225], v[28:31], v[40:43]
	v_mfma_f32_16x16x32_bf16 v[96:99], v[242:245], v[60:63], v[8:11]
	v_mfma_f32_16x16x32_bf16 v[8:11], v[198:201], v[246:249], v[44:47]
	v_mfma_f32_16x16x32_bf16 v[84:87], v[218:221], v[250:253], v[8:11]
	v_mfma_f32_16x16x32_bf16 v[8:11], v[222:225], v[246:249], v[48:51]
	v_mfma_f32_16x16x32_bf16 v[80:83], v[242:245], v[250:253], v[8:11]
	v_mfma_f32_16x16x32_bf16 v[8:11], v[198:201], v[206:209], v[52:55]
	v_mfma_f32_16x16x32_bf16 v[68:71], v[218:221], v[214:217], v[8:11]
	v_mfma_f32_16x16x32_bf16 v[8:11], v[222:225], v[206:209], v[56:59]
	v_mfma_f32_16x16x32_bf16 v[116:119], v[218:221], v[24:27], v[64:67]
	v_mfma_f32_16x16x32_bf16 v[64:67], v[242:245], v[214:217], v[8:11]
	s_setprio 0
	s_barrier
	s_mov_b32 m0, s59
	s_nop 2
	v_lshl_add_u64 v[8:9], v[136:137], 0, s[82:83]
	s_add_u32 s18, s16, 0x18080
	ds_read_b128 v[48:51], v141 offset:49152
	ds_read_b128 v[178:181], v141 offset:50176
	ds_read_b128 v[206:209], v141 offset:51200
	ds_read_b128 v[214:217], v141 offset:52224
	ds_read_b128 v[226:229], v141 offset:53248
	ds_read_b128 v[238:241], v141 offset:54272
	ds_read_b128 v[246:249], v141 offset:55296
	ds_read_b128 v[250:253], v141 offset:56320
	global_load_lds_dwordx4 v[8:9], off
	v_lshl_add_u64 v[8:9], v[202:203], 0, s[82:83]
	s_mov_b32 m0, s55
	s_addc_u32 s19, s17, 0
	global_load_lds_dwordx4 v[8:9], off
	v_lshl_add_u64 v[8:9], s[18:19], 0, v[132:133]
	s_mov_b32 m0, s56
	s_nop 0
	global_load_lds_dwordx4 v[8:9], off
	v_lshl_add_u64 v[8:9], s[18:19], 0, v[128:129]
	s_mov_b32 m0, s58
	s_nop 0
	global_load_lds_dwordx4 v[8:9], off
	v_lshl_add_u64 v[8:9], v[232:233], 0, s[82:83]
	s_mov_b32 m0, s35
	s_nop 0
	global_load_lds_dwordx4 v[8:9], off nt
	v_lshl_add_u64 v[8:9], v[210:211], 0, s[82:83]
	s_mov_b32 m0, s36
	s_nop 0
	global_load_lds_dwordx4 v[8:9], off nt
	s_waitcnt vmcnt(8)
	s_waitcnt lgkmcnt(0)
	s_barrier
	s_setprio 1
	s_waitcnt lgkmcnt(0)
	v_mfma_f32_16x16x32_bf16 v[0:3], v[170:173], v[48:51], v[0:3]
	v_mfma_f32_16x16x32_bf16 v[60:63], v[174:177], v[178:181], v[0:3]
	v_mfma_f32_16x16x32_bf16 v[0:3], v[190:193], v[48:51], v[4:7]
	v_mfma_f32_16x16x32_bf16 v[56:59], v[194:197], v[178:181], v[0:3]
	v_mfma_f32_16x16x32_bf16 v[0:3], v[170:173], v[206:209], v[154:157]
	v_mfma_f32_16x16x32_bf16 v[44:47], v[174:177], v[214:217], v[0:3]
	v_mfma_f32_16x16x32_bf16 v[0:3], v[190:193], v[206:209], v[158:161]
	v_mfma_f32_16x16x32_bf16 v[40:43], v[194:197], v[214:217], v[0:3]
	v_mfma_f32_16x16x32_bf16 v[0:3], v[170:173], v[226:229], v[162:165]
	v_mfma_f32_16x16x32_bf16 v[28:31], v[174:177], v[238:241], v[0:3]
	v_mfma_f32_16x16x32_bf16 v[0:3], v[190:193], v[226:229], v[166:169]
	v_mfma_f32_16x16x32_bf16 v[24:27], v[194:197], v[238:241], v[0:3]
	v_mfma_f32_16x16x32_bf16 v[0:3], v[170:173], v[246:249], v[12:15]
	v_mfma_f32_16x16x32_bf16 v[12:15], v[174:177], v[250:253], v[0:3]
	v_mfma_f32_16x16x32_bf16 v[0:3], v[190:193], v[246:249], v[16:19]
	v_mfma_f32_16x16x32_bf16 v[8:11], v[194:197], v[250:253], v[0:3]
	s_setprio 0
	s_setprio 1
	v_mfma_f32_16x16x32_bf16 v[0:3], v[198:201], v[48:51], v[20:23]
	v_mfma_f32_16x16x32_bf16 v[52:55], v[218:221], v[178:181], v[0:3]
	v_mfma_f32_16x16x32_bf16 v[0:3], v[222:225], v[48:51], v[32:35]
	v_mfma_f32_16x16x32_bf16 v[48:51], v[242:245], v[178:181], v[0:3]
	v_mfma_f32_16x16x32_bf16 v[0:3], v[198:201], v[206:209], v[36:39]
	v_mfma_f32_16x16x32_bf16 v[36:39], v[218:221], v[214:217], v[0:3]
	v_mfma_f32_16x16x32_bf16 v[0:3], v[222:225], v[206:209], v[142:145]
	v_mfma_f32_16x16x32_bf16 v[32:35], v[242:245], v[214:217], v[0:3]
	v_mfma_f32_16x16x32_bf16 v[0:3], v[198:201], v[226:229], v[182:185]
	v_mfma_f32_16x16x32_bf16 v[20:23], v[218:221], v[238:241], v[0:3]
	v_mfma_f32_16x16x32_bf16 v[0:3], v[222:225], v[226:229], v[186:189]
	v_mfma_f32_16x16x32_bf16 v[16:19], v[242:245], v[238:241], v[0:3]
	v_mfma_f32_16x16x32_bf16 v[0:3], v[198:201], v[246:249], v[146:149]
	v_mfma_f32_16x16x32_bf16 v[4:7], v[218:221], v[250:253], v[0:3]
	v_mfma_f32_16x16x32_bf16 v[0:3], v[222:225], v[246:249], v[150:153]
	v_mfma_f32_16x16x32_bf16 v[0:3], v[242:245], v[250:253], v[0:3]
	s_setprio 0
	s_barrier
	s_andn2_b64 vcc, exec, s[12:13]
	s_cbranch_vccnz .LBB0_328
	s_barrier
